# B-prep QK-norm row sums and remaining gMLP sums: bpermute butterflies replaced in place by DPP adds + permlane swaps
# baseline (speedup 1.0000x reference)
; __device__ __forceinline__ unsigned pk2(float lo, float hi) { const f32x2 v = {lo, hi}; const bf16x2_t b = __builtin_convertvector(v, bf16x2_t); return __builtin_bit_cast(unsigned, b); }
; __device__ __forceinline__ void bprep_item(Frame& F, const Args& a, int l, int item, const bf16* P, bf16* QB, bf16* KB, bf16* VT, float* QS) {
;     ...
;         for (int j = 0; j < 4; ++j) {
;             float ss = (x[j][0] * x[j][0] + x[j][1] * x[j][1]) + (x[j][2] * x[j][2] + x[j][3] * x[j][3]);
; #pragma unroll
;             for (int o = 1; o < 32; o <<= 1) ss += __shfl_xor(ss, o);
;             const float rs = 1.0f / sqrtf(ss * (1.f / 128.f) + 1e-6f);
;             if (j < 2) { const f32x4 y = x[j] * rs * qg * qs;
;                 if (!samp) *(u32x2*)(QB + (size_t)row * BW + j * 256 + 4 * lane) = (u32x2){pk2(y[0], y[1]), pk2(y[2], y[3])};
;                 else *(f32x4*)(QS + (size_t)r * BW + j * 256 + 4 * lane) = y; }
.LBB0_225:
	s_waitcnt vmcnt(0)
	v_lshlrev_b32_e32 v39, 16, v13
	v_lshlrev_b32_e32 v38, 16, v12
	v_and_b32_e32 v13, 0xffff0000, v13
	v_and_b32_e32 v12, 0xffff0000, v12
	v_pk_mul_f32 v[40:41], v[12:13], v[12:13]
	v_and_b32_e32 v34, 64, v218
	v_pk_fma_f32 v[40:41], v[38:39], v[38:39], v[40:41]
	v_add_u32_e32 v34, 64, v34
	v_add_f32_e32 v40, v40, v41
	v_xor_b32_e32 v41, 1, v218
	v_cmp_lt_i32_e32 vcc, v41, v34
	v_lshl_add_u64 v[72:73], v[18:19], 1, s[14:15]
	s_nop 0
	v_cndmask_b32_e32 v41, v218, v41, vcc
	v_lshlrev_b32_e32 v82, 2, v41
	s_waitcnt lgkmcnt(0)
	s_nop 1
	v_add_f32_dpp v40, v40, v40 quad_perm:[1,0,3,2] row_mask:0xf bank_mask:0xf
	v_xor_b32_e32 v41, 2, v218
	v_cmp_lt_i32_e32 vcc, v41, v34
	s_nop 1
	v_cndmask_b32_e32 v41, v218, v41, vcc
	v_lshlrev_b32_e32 v83, 2, v41
	s_waitcnt lgkmcnt(0)
	s_nop 1
	v_add_f32_dpp v40, v40, v40 quad_perm:[2,3,0,1] row_mask:0xf bank_mask:0xf
	v_xor_b32_e32 v41, 4, v218
	v_cmp_lt_i32_e32 vcc, v41, v34
	s_nop 1
	v_cndmask_b32_e32 v41, v218, v41, vcc
	v_lshlrev_b32_e32 v84, 2, v41
	s_waitcnt lgkmcnt(0)
	s_nop 1
	v_add_f32_dpp v40, v40, v40 row_half_mirror row_mask:0xf bank_mask:0xf
	v_xor_b32_e32 v41, 8, v218
	v_cmp_lt_i32_e32 vcc, v41, v34
	s_nop 1
	v_cndmask_b32_e32 v41, v218, v41, vcc
	v_lshlrev_b32_e32 v85, 2, v41
	s_waitcnt lgkmcnt(0)
	s_nop 1
	v_add_f32_dpp v40, v40, v40 row_mirror row_mask:0xf bank_mask:0xf
	v_xor_b32_e32 v41, 16, v218
	v_cmp_lt_i32_e32 vcc, v41, v34
	s_nop 1
	v_cndmask_b32_e32 v34, v218, v41, vcc
	v_lshlrev_b32_e32 v86, 2, v34
	s_waitcnt lgkmcnt(0)
	v_mov_b32_e32 v34, v40
	s_nop 1
	v_permlane16_swap_b32 v34, v40
	v_add_f32_e32 v34, v34, v40
	v_fmamk_f32 v34, v34, 0x3c000000, v212
	v_mul_f32_e32 v40, 0x4f800000, v34
	v_cmp_gt_f32_e32 vcc, s67, v34
	s_nop 1
	v_cndmask_b32_e32 v34, v34, v40, vcc
	v_sqrt_f32_e32 v40, v34
	s_nop 0
	v_add_u32_e32 v41, -1, v40
	v_fma_f32 v74, -v41, v40, v34
	v_cmp_ge_f32_e64 s[0:1], 0, v74
	v_add_u32_e32 v74, 1, v40
	s_nop 0
	v_cndmask_b32_e64 v41, v40, v41, s[0:1]
	v_fma_f32 v40, -v74, v40, v34
	v_cmp_lt_f32_e64 s[0:1], 0, v40
	s_nop 1
	v_cndmask_b32_e64 v40, v41, v74, s[0:1]
	v_mul_f32_e32 v41, 0x37800000, v40
	v_cndmask_b32_e32 v40, v40, v41, vcc
	v_cmp_class_f32_e32 vcc, v34, v213
	v_lshlrev_b64 v[74:75], 10, v[10:11]
	s_nop 0
	v_cndmask_b32_e32 v34, v40, v34, vcc
	v_div_scale_f32 v80, s[0:1], v34, v34, 1.0
	v_rcp_f32_e32 v81, v80
	s_mov_b64 s[0:1], 0x32e00000
	v_lshl_add_u64 v[40:41], v[72:73], 0, s[0:1]
	s_mov_b32 s0, 0x3e0293ee
	v_fma_f32 v10, -v80, v81, 1.0
	v_fmac_f32_e32 v81, v10, v81
	v_div_scale_f32 v10, vcc, 1.0, v34, 1.0
	v_mul_f32_e32 v11, v10, v81
	v_fma_f32 v87, -v80, v11, v10
	v_fmac_f32_e32 v11, v87, v81
	v_fma_f32 v10, -v80, v11, v10
	v_div_fmas_f32 v10, v10, v81, v11
	v_div_fixup_f32 v10, v10, v34, 1.0
	v_mov_b32_e32 v80, v39
	v_mov_b32_e32 v81, v13
	v_mov_b32_e32 v39, v12
	v_pk_mul_f32 v[80:81], v[10:11], v[80:81] op_sel_hi:[0,1]
	v_pk_mul_f32 v[10:11], v[10:11], v[38:39] op_sel_hi:[0,1]
	v_pk_mul_f32 v[10:11], v[6:7], v[10:11]
	v_pk_mul_f32 v[12:13], v[8:9], v[80:81]
	v_cndmask_b32_e64 v34, 0, 1, s[4:5]
	v_lshl_add_u64 v[78:79], v[40:41], 0, v[74:75]
	v_pk_mul_f32 v[12:13], v[12:13], s[0:1] op_sel_hi:[1,0]
	v_pk_mul_f32 v[10:11], v[10:11], s[0:1] op_sel_hi:[1,0]
	v_cmp_ne_u32_e64 s[0:1], 1, v34
	s_andn2_b64 vcc, exec, s[4:5]
	s_mov_b64 s[4:5], -1
	s_cbranch_vccnz .LBB0_227
	v_cvt_pk_bf16_f32 v38, v10, v11
	v_cvt_pk_bf16_f32 v39, v12, v13
	s_mov_b64 s[4:5], 0
	global_store_dwordx2 v[78:79], v[38:39], off

; __device__ __forceinline__ unsigned pk2(float lo, float hi) { const f32x2 v = {lo, hi}; const bf16x2_t b = __builtin_convertvector(v, bf16x2_t); return __builtin_bit_cast(unsigned, b); }
; __device__ __forceinline__ void bprep_item(Frame& F, const Args& a, int l, int item, const bf16* P, bf16* QB, bf16* KB, bf16* VT, float* QS) {
;     ...
;         for (int j = 0; j < 4; ++j) {
;             float ss = (x[j][0] * x[j][0] + x[j][1] * x[j][1]) + (x[j][2] * x[j][2] + x[j][3] * x[j][3]);
; #pragma unroll
;             for (int o = 1; o < 32; o <<= 1) ss += __shfl_xor(ss, o);
;             const float rs = 1.0f / sqrtf(ss * (1.f / 128.f) + 1e-6f);
;             if (j < 2) { const f32x4 y = x[j] * rs * qg * qs;
;                 if (!samp) *(u32x2*)(QB + (size_t)row * BW + j * 256 + 4 * lane) = (u32x2){pk2(y[0], y[1]), pk2(y[2], y[3])};
;                 else *(f32x4*)(QS + (size_t)r * BW + j * 256 + 4 * lane) = y; }
.LBB0_229:
	s_nop 1
	v_and_b32_e32 v13, 0xffff0000, v77
	v_and_b32_e32 v12, 0xffff0000, v76
	v_lshlrev_b32_e32 v11, 16, v77
	v_lshlrev_b32_e32 v10, 16, v76
	v_pk_mul_f32 v[76:77], v[12:13], v[12:13]
	s_nop 0
	v_pk_fma_f32 v[76:77], v[10:11], v[10:11], v[76:77]
	s_nop 0
	v_add_f32_e32 v33, v76, v77
	v_mov_b32_e32 v76, v11
	v_mov_b32_e32 v77, v13
	s_waitcnt lgkmcnt(0)
	s_nop 1
	v_add_f32_dpp v33, v33, v33 quad_perm:[1,0,3,2] row_mask:0xf bank_mask:0xf
	s_waitcnt lgkmcnt(0)
	s_nop 1
	v_add_f32_dpp v33, v33, v33 quad_perm:[2,3,0,1] row_mask:0xf bank_mask:0xf
	s_waitcnt lgkmcnt(0)
	s_nop 1
	v_add_f32_dpp v33, v33, v33 row_half_mirror row_mask:0xf bank_mask:0xf
	s_waitcnt lgkmcnt(0)
	s_nop 1
	v_add_f32_dpp v33, v33, v33 row_mirror row_mask:0xf bank_mask:0xf
	s_waitcnt lgkmcnt(0)
	v_mov_b32_e32 v34, v33
	s_nop 1
	v_permlane16_swap_b32 v34, v33
	v_add_f32_e32 v33, v33, v34
	v_fmamk_f32 v33, v33, 0x3c000000, v212
	v_mul_f32_e32 v34, 0x4f800000, v33
	v_cmp_gt_f32_e32 vcc, s67, v33
	s_nop 1
	v_cndmask_b32_e32 v33, v33, v34, vcc
	v_sqrt_f32_e32 v34, v33
	s_nop 0
	v_add_u32_e32 v11, -1, v34
	v_add_u32_e32 v13, 1, v34
	v_fma_f32 v87, -v11, v34, v33
	v_fma_f32 v88, -v13, v34, v33
	v_cmp_ge_f32_e64 s[4:5], 0, v87
	s_nop 1
	v_cndmask_b32_e64 v11, v34, v11, s[4:5]
	v_cmp_lt_f32_e64 s[4:5], 0, v88
	s_nop 1
	v_cndmask_b32_e64 v11, v11, v13, s[4:5]
	v_mul_f32_e32 v13, 0x37800000, v11
	v_cndmask_b32_e32 v11, v11, v13, vcc
	v_cmp_class_f32_e32 vcc, v33, v213
	s_nop 1
	v_cndmask_b32_e32 v13, v11, v33, vcc
	v_div_scale_f32 v33, s[4:5], v13, v13, 1.0
	v_rcp_f32_e32 v34, v33
	v_mov_b32_e32 v11, v12
	v_div_scale_f32 v12, vcc, 1.0, v13, 1.0
	v_fma_f32 v87, -v33, v34, 1.0
	v_fmac_f32_e32 v34, v87, v34
	v_mul_f32_e32 v87, v12, v34
	v_fma_f32 v88, -v33, v87, v12
	v_fmac_f32_e32 v87, v88, v34
	v_fma_f32 v12, -v33, v87, v12
	v_div_fmas_f32 v12, v12, v34, v87
	v_div_fixup_f32 v12, v12, v13, 1.0
	v_pk_mul_f32 v[76:77], v[12:13], v[76:77] op_sel_hi:[0,1]
	v_pk_mul_f32 v[10:11], v[12:13], v[10:11] op_sel_hi:[0,1]
	v_pk_mul_f32 v[10:11], v[6:7], v[10:11]
	v_pk_mul_f32 v[12:13], v[8:9], v[76:77]
	s_mov_b32 s4, 0x3e0293ee
	s_and_b64 vcc, exec, s[0:1]
	v_pk_mul_f32 v[12:13], v[12:13], s[4:5] op_sel_hi:[1,0]
	v_pk_mul_f32 v[10:11], v[10:11], s[4:5] op_sel_hi:[1,0]
	s_mov_b64 s[4:5], -1
	s_cbranch_vccnz .LBB0_231
	v_cvt_pk_bf16_f32 v76, v10, v11
	v_cvt_pk_bf16_f32 v77, v12, v13
	s_mov_b64 s[4:5], 0
	global_store_dwordx2 v[78:79], v[76:77], off offset:512

; __device__ __forceinline__ unsigned pk2(float lo, float hi) { const f32x2 v = {lo, hi}; const bf16x2_t b = __builtin_convertvector(v, bf16x2_t); return __builtin_bit_cast(unsigned, b); }
; __device__ __forceinline__ void bprep_item(Frame& F, const Args& a, int l, int item, const bf16* P, bf16* QB, bf16* KB, bf16* VT, float* QS) {
;     ...
;         for (int j = 0; j < 4; ++j) {
;             float ss = (x[j][0] * x[j][0] + x[j][1] * x[j][1]) + (x[j][2] * x[j][2] + x[j][3] * x[j][3]);
; #pragma unroll
;             for (int o = 1; o < 32; o <<= 1) ss += __shfl_xor(ss, o);
;             const float rs = 1.0f / sqrtf(ss * (1.f / 128.f) + 1e-6f);
;             if (j < 2) { const f32x4 y = x[j] * rs * qg * qs;
;                 if (!samp) *(u32x2*)(QB + (size_t)row * BW + j * 256 + 4 * lane) = (u32x2){pk2(y[0], y[1]), pk2(y[2], y[3])};
;                 else *(f32x4*)(QS + (size_t)r * BW + j * 256 + 4 * lane) = y; }
;             else { const f32x4 y = x[j] * rs * kg; *(f32x4*)(ko + (j - 2) * 256 + 4 * lane) = y;
;                 if (!samp) *(u32x2*)(KB + (size_t)row * BW + (j - 2) * 256 + 4 * lane) = (u32x2){pk2(y[0], y[1]), pk2(y[2], y[3])}; }
;         }
.LBB0_233:
	s_nop 1
	v_and_b32_e32 v13, 0xffff0000, v37
	v_and_b32_e32 v12, 0xffff0000, v36
	v_lshlrev_b32_e32 v11, 16, v37
	v_lshlrev_b32_e32 v10, 16, v36
	v_pk_mul_f32 v[36:37], v[12:13], v[12:13]
	s_mov_b64 s[4:5], 0x33600000
	v_pk_fma_f32 v[36:37], v[10:11], v[10:11], v[36:37]
	v_lshl_add_u64 v[70:71], v[18:19], 2, v[70:71]
	v_add_f32_e32 v33, v36, v37
	v_lshl_add_u64 v[36:37], v[72:73], 0, s[4:5]
	v_lshl_add_u64 v[72:73], v[36:37], 0, v[74:75]
	v_mov_b32_e32 v74, v10
	v_mov_b32_e32 v75, v12
	s_waitcnt lgkmcnt(0)
	s_nop 1
	v_add_f32_dpp v33, v33, v33 quad_perm:[1,0,3,2] row_mask:0xf bank_mask:0xf
	s_waitcnt lgkmcnt(0)
	s_nop 1
	v_add_f32_dpp v33, v33, v33 quad_perm:[2,3,0,1] row_mask:0xf bank_mask:0xf
	s_waitcnt lgkmcnt(0)
	s_nop 1
	v_add_f32_dpp v33, v33, v33 row_half_mirror row_mask:0xf bank_mask:0xf
	s_waitcnt lgkmcnt(0)
	s_nop 1
	v_add_f32_dpp v33, v33, v33 row_mirror row_mask:0xf bank_mask:0xf
	s_waitcnt lgkmcnt(0)
	v_mov_b32_e32 v34, v33
	s_nop 1
	v_permlane16_swap_b32 v34, v33
	v_add_f32_e32 v33, v33, v34
	v_fmamk_f32 v33, v33, 0x3c000000, v212
	v_mul_f32_e32 v34, 0x4f800000, v33
	v_cmp_gt_f32_e32 vcc, s67, v33
	s_nop 1
	v_cndmask_b32_e32 v33, v33, v34, vcc
	v_sqrt_f32_e32 v34, v33
	s_nop 0
	v_add_u32_e32 v10, -1, v34
	v_add_u32_e32 v12, 1, v34
	v_fma_f32 v76, -v10, v34, v33
	v_fma_f32 v77, -v12, v34, v33
	v_cmp_ge_f32_e64 s[4:5], 0, v76
	s_nop 1
	v_cndmask_b32_e64 v10, v34, v10, s[4:5]
	v_cmp_lt_f32_e64 s[4:5], 0, v77
	s_nop 1
	v_cndmask_b32_e64 v10, v10, v12, s[4:5]
	v_mul_f32_e32 v12, 0x37800000, v10
	v_cndmask_b32_e32 v10, v10, v12, vcc
	v_cmp_class_f32_e32 vcc, v33, v213
	v_mov_b32_e32 v12, v11
	s_nop 0
	v_cndmask_b32_e32 v10, v10, v33, vcc
	v_div_scale_f32 v33, s[4:5], v10, v10, 1.0
	v_rcp_f32_e32 v34, v33
	v_div_scale_f32 v11, vcc, 1.0, v10, 1.0
	v_fma_f32 v76, -v33, v34, 1.0
	v_fmac_f32_e32 v34, v76, v34
	v_mul_f32_e32 v76, v11, v34
	v_fma_f32 v77, -v33, v76, v11
	v_fmac_f32_e32 v76, v77, v34
	v_fma_f32 v11, -v33, v76, v11
	v_div_fmas_f32 v11, v11, v34, v76
	v_div_fixup_f32 v10, v11, v10, 1.0
	v_pk_mul_f32 v[74:75], v[10:11], v[74:75] op_sel_hi:[0,1]
	v_pk_mul_f32 v[10:11], v[10:11], v[12:13] op_sel_hi:[0,1]
	v_pk_mul_f32 v[12:13], v[4:5], v[10:11]
	v_pk_mul_f32 v[10:11], v[2:3], v[74:75]
	s_and_b64 vcc, exec, s[0:1]
	global_store_dwordx4 v[70:71], v[10:13], off
	s_cbranch_vccnz .LBB0_235
	s_nop 0
	v_cvt_pk_bf16_f32 v10, v10, v11
	v_cvt_pk_bf16_f32 v11, v12, v13
	global_store_dwordx2 v[72:73], v[10:11], off
.LBB0_235:
	s_nop 0
	v_and_b32_e32 v13, 0xffff0000, v15
	v_and_b32_e32 v12, 0xffff0000, v14
	v_lshlrev_b32_e32 v11, 16, v15
	v_lshlrev_b32_e32 v10, 16, v14
	v_pk_mul_f32 v[14:15], v[12:13], v[12:13]
	s_nop 0
	v_pk_fma_f32 v[14:15], v[10:11], v[10:11], v[14:15]
	s_nop 0
	v_add_f32_e32 v14, v14, v15
	s_waitcnt lgkmcnt(0)
	s_nop 1
	v_add_f32_dpp v14, v14, v14 quad_perm:[1,0,3,2] row_mask:0xf bank_mask:0xf
	s_waitcnt lgkmcnt(0)
	s_nop 1
	v_add_f32_dpp v14, v14, v14 quad_perm:[2,3,0,1] row_mask:0xf bank_mask:0xf
	s_waitcnt lgkmcnt(0)
	s_nop 1
	v_add_f32_dpp v14, v14, v14 row_half_mirror row_mask:0xf bank_mask:0xf
	s_waitcnt lgkmcnt(0)
	s_nop 1
	v_add_f32_dpp v14, v14, v14 row_mirror row_mask:0xf bank_mask:0xf
	s_waitcnt lgkmcnt(0)
	v_mov_b32_e32 v15, v14
	s_nop 1
	v_permlane16_swap_b32 v15, v14
	v_add_f32_e32 v14, v14, v15
	v_fmamk_f32 v14, v14, 0x3c000000, v212
	v_mul_f32_e32 v15, 0x4f800000, v14
	v_cmp_gt_f32_e32 vcc, s67, v14
	s_nop 1
	v_cndmask_b32_e32 v33, v14, v15, vcc
	v_sqrt_f32_e32 v34, v33
	v_mov_b32_e32 v14, v10
	v_mov_b32_e32 v15, v12
	v_add_u32_e32 v10, -1, v34
	v_add_u32_e32 v12, 1, v34
	v_fma_f32 v74, -v10, v34, v33
	v_fma_f32 v75, -v12, v34, v33
	v_cmp_ge_f32_e64 s[4:5], 0, v74
	s_nop 1
	v_cndmask_b32_e64 v10, v34, v10, s[4:5]
	v_cmp_lt_f32_e64 s[4:5], 0, v75
	s_nop 1
	v_cndmask_b32_e64 v10, v10, v12, s[4:5]
	v_mul_f32_e32 v12, 0x37800000, v10
	v_cndmask_b32_e32 v10, v10, v12, vcc
	v_cmp_class_f32_e32 vcc, v33, v213
	v_mov_b32_e32 v12, v11
	s_nop 0
	v_cndmask_b32_e32 v10, v10, v33, vcc
	v_div_scale_f32 v33, s[4:5], v10, v10, 1.0
	v_rcp_f32_e32 v34, v33
	v_div_scale_f32 v11, vcc, 1.0, v10, 1.0
	v_fma_f32 v74, -v33, v34, 1.0
	v_fmac_f32_e32 v34, v74, v34
	v_mul_f32_e32 v74, v11, v34
	v_fma_f32 v75, -v33, v74, v11
	v_fmac_f32_e32 v74, v75, v34
	v_fma_f32 v11, -v33, v74, v11
	v_div_fmas_f32 v11, v11, v34, v74
	v_div_fixup_f32 v10, v11, v10, 1.0
	v_pk_mul_f32 v[14:15], v[10:11], v[14:15] op_sel_hi:[0,1]
	v_pk_mul_f32 v[10:11], v[10:11], v[12:13] op_sel_hi:[0,1]
	v_pk_mul_f32 v[12:13], v[4:5], v[10:11]
	v_pk_mul_f32 v[10:11], v[2:3], v[14:15]
	s_and_b64 vcc, exec, s[0:1]
	global_store_dwordx4 v[70:71], v[10:13], off offset:1024
	s_cbranch_vccnz .LBB0_237
	s_nop 0
	v_cvt_pk_bf16_f32 v10, v10, v11
	v_cvt_pk_bf16_f32 v11, v12, v13
	global_store_dwordx2 v[72:73], v[10:11], off offset:512

; __device__ __forceinline__ unsigned pk2(float lo, float hi) { const f32x2 v = {lo, hi}; const bf16x2_t b = __builtin_convertvector(v, bf16x2_t); return __builtin_bit_cast(unsigned, b); }
; __device__ __forceinline__ void bprep_item(Frame& F, const Args& a, int l, int item, const bf16* P, bf16* QB, bf16* KB, bf16* VT, float* QS) {
;     ...
;         for (int j = 0; j < 4; ++j) {
;             float ss = (x[j][0] * x[j][0] + x[j][1] * x[j][1]) + (x[j][2] * x[j][2] + x[j][3] * x[j][3]);
; #pragma unroll
;             for (int o = 1; o < 32; o <<= 1) ss += __shfl_xor(ss, o);
;             const float rs = 1.0f / sqrtf(ss * (1.f / 128.f) + 1e-6f);
;             if (j < 2) { const f32x4 y = x[j] * rs * qg * qs;
;                 if (!samp) *(u32x2*)(QB + (size_t)row * BW + j * 256 + 4 * lane) = (u32x2){pk2(y[0], y[1]), pk2(y[2], y[3])};
;                 else *(f32x4*)(QS + (size_t)r * BW + j * 256 + 4 * lane) = y; }
.LBB0_243:
	v_and_b32_e32 v71, 0xffff0000, v65
	v_and_b32_e32 v70, 0xffff0000, v64
	v_lshlrev_b32_e32 v13, 16, v65
	v_lshlrev_b32_e32 v12, 16, v64
	v_pk_mul_f32 v[16:17], v[70:71], v[70:71]
	s_nop 0
	v_pk_fma_f32 v[16:17], v[12:13], v[12:13], v[16:17]
	s_nop 0
	v_add_f32_e32 v16, v16, v17
	s_waitcnt lgkmcnt(0)
	s_nop 1
	v_add_f32_dpp v16, v16, v16 quad_perm:[1,0,3,2] row_mask:0xf bank_mask:0xf
	s_waitcnt lgkmcnt(0)
	s_nop 1
	v_add_f32_dpp v16, v16, v16 quad_perm:[2,3,0,1] row_mask:0xf bank_mask:0xf
	s_waitcnt lgkmcnt(0)
	s_nop 1
	v_add_f32_dpp v16, v16, v16 row_half_mirror row_mask:0xf bank_mask:0xf
	s_waitcnt lgkmcnt(0)
	s_nop 1
	v_add_f32_dpp v33, v16, v16 row_mirror row_mask:0xf bank_mask:0xf
	v_lshlrev_b64 v[16:17], 10, v[10:11]
	s_waitcnt lgkmcnt(0)
	v_mov_b32_e32 v64, v33
	v_mov_b32_e32 v10, v33
	s_nop 1
	v_permlane16_swap_b32 v64, v10
	v_add_f32_e32 v10, v10, v64
	v_fmamk_f32 v10, v10, 0x3c000000, v212
	v_mul_f32_e32 v11, 0x4f800000, v10
	v_cmp_gt_f32_e32 vcc, s67, v10
	v_lshl_add_u64 v[64:65], v[40:41], 0, v[16:17]
	s_nop 0
	v_cndmask_b32_e32 v33, v10, v11, vcc
	v_sqrt_f32_e32 v72, v33
	v_mov_b32_e32 v10, v13
	v_mov_b32_e32 v11, v71
	v_add_u32_e32 v13, -1, v72
	v_add_u32_e32 v71, 1, v72
	v_fma_f32 v73, -v13, v72, v33
	v_fma_f32 v74, -v71, v72, v33
	v_cmp_ge_f32_e64 s[4:5], 0, v73
	s_nop 1
	v_cndmask_b32_e64 v13, v72, v13, s[4:5]
	v_cmp_lt_f32_e64 s[4:5], 0, v74
	s_nop 1
	v_cndmask_b32_e64 v13, v13, v71, s[4:5]
	v_mul_f32_e32 v71, 0x37800000, v13
	v_cndmask_b32_e32 v13, v13, v71, vcc
	v_cmp_class_f32_e32 vcc, v33, v213
	s_nop 1
	v_cndmask_b32_e32 v33, v13, v33, vcc
	v_div_scale_f32 v71, s[4:5], v33, v33, 1.0
	v_rcp_f32_e32 v72, v71
	v_mov_b32_e32 v13, v70
	v_div_scale_f32 v70, vcc, 1.0, v33, 1.0
	v_fma_f32 v73, -v71, v72, 1.0
	v_fmac_f32_e32 v72, v73, v72
	v_mul_f32_e32 v73, v70, v72
	v_fma_f32 v74, -v71, v73, v70
	v_fmac_f32_e32 v73, v74, v72
	v_fma_f32 v70, -v71, v73, v70
	v_div_fmas_f32 v70, v70, v72, v73
	v_div_fixup_f32 v70, v70, v33, 1.0
	v_pk_mul_f32 v[10:11], v[70:71], v[10:11] op_sel_hi:[0,1]
	v_pk_mul_f32 v[12:13], v[70:71], v[12:13] op_sel_hi:[0,1]
	v_pk_mul_f32 v[70:71], v[6:7], v[12:13]
	v_pk_mul_f32 v[10:11], v[8:9], v[10:11]
	s_mov_b32 s4, 0x3e0293ee
	s_and_b64 vcc, exec, s[0:1]
	v_pk_mul_f32 v[12:13], v[10:11], s[4:5] op_sel_hi:[1,0]
	v_pk_mul_f32 v[10:11], v[70:71], s[4:5] op_sel_hi:[1,0]
	s_mov_b64 s[4:5], -1
	s_cbranch_vccnz .LBB0_245
	v_cvt_pk_bf16_f32 v70, v10, v11
	v_cvt_pk_bf16_f32 v71, v12, v13
	s_mov_b64 s[4:5], 0
	global_store_dwordx2 v[64:65], v[70:71], off

; __device__ __forceinline__ unsigned pk2(float lo, float hi) { const f32x2 v = {lo, hi}; const bf16x2_t b = __builtin_convertvector(v, bf16x2_t); return __builtin_bit_cast(unsigned, b); }
; __device__ __forceinline__ void bprep_item(Frame& F, const Args& a, int l, int item, const bf16* P, bf16* QB, bf16* KB, bf16* VT, float* QS) {
;     ...
;         for (int j = 0; j < 4; ++j) {
;             float ss = (x[j][0] * x[j][0] + x[j][1] * x[j][1]) + (x[j][2] * x[j][2] + x[j][3] * x[j][3]);
; #pragma unroll
;             for (int o = 1; o < 32; o <<= 1) ss += __shfl_xor(ss, o);
;             const float rs = 1.0f / sqrtf(ss * (1.f / 128.f) + 1e-6f);
;             if (j < 2) { const f32x4 y = x[j] * rs * qg * qs;
;                 if (!samp) *(u32x2*)(QB + (size_t)row * BW + j * 256 + 4 * lane) = (u32x2){pk2(y[0], y[1]), pk2(y[2], y[3])};
;                 else *(f32x4*)(QS + (size_t)r * BW + j * 256 + 4 * lane) = y; }
.LBB0_247:
	s_nop 1
	v_and_b32_e32 v13, 0xffff0000, v63
	v_and_b32_e32 v12, 0xffff0000, v62
	v_lshlrev_b32_e32 v11, 16, v63
	v_lshlrev_b32_e32 v10, 16, v62
	v_pk_mul_f32 v[62:63], v[12:13], v[12:13]
	s_nop 0
	v_pk_fma_f32 v[62:63], v[10:11], v[10:11], v[62:63]
	s_nop 0
	v_add_f32_e32 v33, v62, v63
	v_mov_b32_e32 v63, v13
	s_waitcnt lgkmcnt(0)
	s_nop 1
	v_add_f32_dpp v33, v33, v33 quad_perm:[1,0,3,2] row_mask:0xf bank_mask:0xf
	s_waitcnt lgkmcnt(0)
	s_nop 1
	v_add_f32_dpp v33, v33, v33 quad_perm:[2,3,0,1] row_mask:0xf bank_mask:0xf
	s_waitcnt lgkmcnt(0)
	s_nop 1
	v_add_f32_dpp v33, v33, v33 row_half_mirror row_mask:0xf bank_mask:0xf
	s_waitcnt lgkmcnt(0)
	s_nop 1
	v_add_f32_dpp v33, v33, v33 row_mirror row_mask:0xf bank_mask:0xf
	s_waitcnt lgkmcnt(0)
	v_mov_b32_e32 v62, v33
	s_nop 1
	v_permlane16_swap_b32 v62, v33
	v_add_f32_e32 v33, v33, v62
	v_fmamk_f32 v33, v33, 0x3c000000, v212
	v_mul_f32_e32 v62, 0x4f800000, v33
	v_cmp_gt_f32_e32 vcc, s67, v33
	s_nop 1
	v_cndmask_b32_e32 v33, v33, v62, vcc
	v_sqrt_f32_e32 v67, v33
	v_mov_b32_e32 v62, v11
	v_add_u32_e32 v11, -1, v67
	v_add_u32_e32 v13, 1, v67
	v_fma_f32 v72, -v11, v67, v33
	v_fma_f32 v73, -v13, v67, v33
	v_cmp_ge_f32_e64 s[4:5], 0, v72
	s_nop 1
	v_cndmask_b32_e64 v11, v67, v11, s[4:5]
	v_cmp_lt_f32_e64 s[4:5], 0, v73
	s_nop 1
	v_cndmask_b32_e64 v11, v11, v13, s[4:5]
	v_mul_f32_e32 v13, 0x37800000, v11
	v_cndmask_b32_e32 v11, v11, v13, vcc
	v_cmp_class_f32_e32 vcc, v33, v213
	s_nop 1
	v_cndmask_b32_e32 v13, v11, v33, vcc
	v_div_scale_f32 v33, s[4:5], v13, v13, 1.0
	v_rcp_f32_e32 v67, v33
	v_mov_b32_e32 v11, v12
	v_div_scale_f32 v12, vcc, 1.0, v13, 1.0
	v_fma_f32 v72, -v33, v67, 1.0
	v_fmac_f32_e32 v67, v72, v67
	v_mul_f32_e32 v72, v12, v67
	v_fma_f32 v73, -v33, v72, v12
	v_fmac_f32_e32 v72, v73, v67
	v_fma_f32 v12, -v33, v72, v12
	v_div_fmas_f32 v12, v12, v67, v72
	v_div_fixup_f32 v12, v12, v13, 1.0
	v_pk_mul_f32 v[62:63], v[12:13], v[62:63] op_sel_hi:[0,1]
	v_pk_mul_f32 v[10:11], v[12:13], v[10:11] op_sel_hi:[0,1]
	v_pk_mul_f32 v[10:11], v[6:7], v[10:11]
	v_pk_mul_f32 v[12:13], v[8:9], v[62:63]
	s_mov_b32 s4, 0x3e0293ee
	s_and_b64 vcc, exec, s[0:1]
	v_pk_mul_f32 v[12:13], v[12:13], s[4:5] op_sel_hi:[1,0]
	v_pk_mul_f32 v[10:11], v[10:11], s[4:5] op_sel_hi:[1,0]
	s_mov_b64 s[4:5], -1
	s_cbranch_vccnz .LBB0_249
	v_cvt_pk_bf16_f32 v62, v10, v11
	v_cvt_pk_bf16_f32 v63, v12, v13
	s_mov_b64 s[4:5], 0
	global_store_dwordx2 v[64:65], v[62:63], off offset:512

; __device__ __forceinline__ unsigned pk2(float lo, float hi) { const f32x2 v = {lo, hi}; const bf16x2_t b = __builtin_convertvector(v, bf16x2_t); return __builtin_bit_cast(unsigned, b); }
; __device__ __forceinline__ void bprep_item(Frame& F, const Args& a, int l, int item, const bf16* P, bf16* QB, bf16* KB, bf16* VT, float* QS) {
;     ...
;         for (int j = 0; j < 4; ++j) {
;             float ss = (x[j][0] * x[j][0] + x[j][1] * x[j][1]) + (x[j][2] * x[j][2] + x[j][3] * x[j][3]);
; #pragma unroll
;             for (int o = 1; o < 32; o <<= 1) ss += __shfl_xor(ss, o);
;             const float rs = 1.0f / sqrtf(ss * (1.f / 128.f) + 1e-6f);
;             if (j < 2) { const f32x4 y = x[j] * rs * qg * qs;
;                 if (!samp) *(u32x2*)(QB + (size_t)row * BW + j * 256 + 4 * lane) = (u32x2){pk2(y[0], y[1]), pk2(y[2], y[3])};
;                 else *(f32x4*)(QS + (size_t)r * BW + j * 256 + 4 * lane) = y; }
;             else { const f32x4 y = x[j] * rs * kg; *(f32x4*)(ko + (j - 2) * 256 + 4 * lane) = y;
;                 if (!samp) *(u32x2*)(KB + (size_t)row * BW + (j - 2) * 256 + 4 * lane) = (u32x2){pk2(y[0], y[1]), pk2(y[2], y[3])}; }
;         }
.LBB0_251:
	s_nop 1
	v_and_b32_e32 v13, 0xffff0000, v61
	v_and_b32_e32 v12, 0xffff0000, v60
	v_lshlrev_b32_e32 v11, 16, v61
	v_lshlrev_b32_e32 v10, 16, v60
	v_pk_mul_f32 v[60:61], v[12:13], v[12:13]
	v_lshl_add_u64 v[14:15], v[18:19], 2, v[14:15]
	v_pk_fma_f32 v[60:61], v[10:11], v[10:11], v[60:61]
	v_lshl_add_u64 v[16:17], v[36:37], 0, v[16:17]
	v_add_f32_e32 v33, v60, v61
	v_mov_b32_e32 v61, v12
	s_waitcnt lgkmcnt(0)
	s_nop 1
	v_add_f32_dpp v33, v33, v33 quad_perm:[1,0,3,2] row_mask:0xf bank_mask:0xf
	s_waitcnt lgkmcnt(0)
	s_nop 1
	v_add_f32_dpp v33, v33, v33 quad_perm:[2,3,0,1] row_mask:0xf bank_mask:0xf
	s_waitcnt lgkmcnt(0)
	s_nop 1
	v_add_f32_dpp v33, v33, v33 row_half_mirror row_mask:0xf bank_mask:0xf
	s_waitcnt lgkmcnt(0)
	s_nop 1
	v_add_f32_dpp v33, v33, v33 row_mirror row_mask:0xf bank_mask:0xf
	s_waitcnt lgkmcnt(0)
	v_mov_b32_e32 v60, v33
	s_nop 1
	v_permlane16_swap_b32 v60, v33
	v_add_f32_e32 v33, v33, v60
	v_fmamk_f32 v33, v33, 0x3c000000, v212
	v_mul_f32_e32 v60, 0x4f800000, v33
	v_cmp_gt_f32_e32 vcc, s67, v33
	s_nop 1
	v_cndmask_b32_e32 v33, v33, v60, vcc
	v_sqrt_f32_e32 v62, v33
	v_mov_b32_e32 v60, v10
	v_add_u32_e32 v10, -1, v62
	v_add_u32_e32 v12, 1, v62
	v_fma_f32 v63, -v10, v62, v33
	v_fma_f32 v64, -v12, v62, v33
	v_cmp_ge_f32_e64 s[4:5], 0, v63
	s_nop 1
	v_cndmask_b32_e64 v10, v62, v10, s[4:5]
	v_cmp_lt_f32_e64 s[4:5], 0, v64
	s_nop 1
	v_cndmask_b32_e64 v10, v10, v12, s[4:5]
	v_mul_f32_e32 v12, 0x37800000, v10
	v_cndmask_b32_e32 v10, v10, v12, vcc
	v_cmp_class_f32_e32 vcc, v33, v213
	v_mov_b32_e32 v12, v11
	s_nop 0
	v_cndmask_b32_e32 v10, v10, v33, vcc
	v_div_scale_f32 v33, s[4:5], v10, v10, 1.0
	v_rcp_f32_e32 v62, v33
	v_div_scale_f32 v11, vcc, 1.0, v10, 1.0
	v_fma_f32 v63, -v33, v62, 1.0
	v_fmac_f32_e32 v62, v63, v62
	v_mul_f32_e32 v63, v11, v62
	v_fma_f32 v64, -v33, v63, v11
	v_fmac_f32_e32 v63, v64, v62
	v_fma_f32 v11, -v33, v63, v11
	v_div_fmas_f32 v11, v11, v62, v63
	v_div_fixup_f32 v10, v11, v10, 1.0
	v_pk_mul_f32 v[60:61], v[10:11], v[60:61] op_sel_hi:[0,1]
	v_pk_mul_f32 v[10:11], v[10:11], v[12:13] op_sel_hi:[0,1]
	v_pk_mul_f32 v[12:13], v[4:5], v[10:11]
	v_pk_mul_f32 v[10:11], v[2:3], v[60:61]
	s_and_b64 vcc, exec, s[0:1]
	global_store_dwordx4 v[14:15], v[10:13], off
	s_cbranch_vccnz .LBB0_253
	s_nop 0
	v_cvt_pk_bf16_f32 v10, v10, v11
	v_cvt_pk_bf16_f32 v11, v12, v13
	global_store_dwordx2 v[16:17], v[10:11], off
.LBB0_253:
	s_nop 0
	v_and_b32_e32 v13, 0xffff0000, v59
	v_and_b32_e32 v12, 0xffff0000, v58
	v_lshlrev_b32_e32 v11, 16, v59
	v_lshlrev_b32_e32 v10, 16, v58
	v_pk_mul_f32 v[58:59], v[12:13], v[12:13]
	s_nop 0
	v_pk_fma_f32 v[58:59], v[10:11], v[10:11], v[58:59]
	s_nop 0
	v_add_f32_e32 v33, v58, v59
	v_mov_b32_e32 v59, v12
	s_waitcnt lgkmcnt(0)
	s_nop 1
	v_add_f32_dpp v33, v33, v33 quad_perm:[1,0,3,2] row_mask:0xf bank_mask:0xf
	s_waitcnt lgkmcnt(0)
	s_nop 1
	v_add_f32_dpp v33, v33, v33 quad_perm:[2,3,0,1] row_mask:0xf bank_mask:0xf
	s_waitcnt lgkmcnt(0)
	s_nop 1
	v_add_f32_dpp v33, v33, v33 row_half_mirror row_mask:0xf bank_mask:0xf
	s_waitcnt lgkmcnt(0)
	s_nop 1
	v_add_f32_dpp v33, v33, v33 row_mirror row_mask:0xf bank_mask:0xf
	s_waitcnt lgkmcnt(0)
	v_mov_b32_e32 v58, v33
	s_nop 1
	v_permlane16_swap_b32 v58, v33
	v_add_f32_e32 v33, v33, v58
	v_fmamk_f32 v33, v33, 0x3c000000, v212
	v_mul_f32_e32 v58, 0x4f800000, v33
	v_cmp_gt_f32_e32 vcc, s67, v33
	s_nop 1
	v_cndmask_b32_e32 v33, v33, v58, vcc
	v_sqrt_f32_e32 v60, v33
	v_mov_b32_e32 v58, v10
	v_add_u32_e32 v10, -1, v60
	v_add_u32_e32 v12, 1, v60
	v_fma_f32 v61, -v10, v60, v33
	v_fma_f32 v62, -v12, v60, v33
	v_cmp_ge_f32_e64 s[4:5], 0, v61
	s_nop 1
	v_cndmask_b32_e64 v10, v60, v10, s[4:5]
	v_cmp_lt_f32_e64 s[4:5], 0, v62
	s_nop 1
	v_cndmask_b32_e64 v10, v10, v12, s[4:5]
	v_mul_f32_e32 v12, 0x37800000, v10
	v_cndmask_b32_e32 v10, v10, v12, vcc
	v_cmp_class_f32_e32 vcc, v33, v213
	v_mov_b32_e32 v12, v11
	s_nop 0
	v_cndmask_b32_e32 v10, v10, v33, vcc
	v_div_scale_f32 v33, s[4:5], v10, v10, 1.0
	v_rcp_f32_e32 v60, v33
	v_div_scale_f32 v11, vcc, 1.0, v10, 1.0
	v_fma_f32 v61, -v33, v60, 1.0
	v_fmac_f32_e32 v60, v61, v60
	v_mul_f32_e32 v61, v11, v60
	v_fma_f32 v62, -v33, v61, v11
	v_fmac_f32_e32 v61, v62, v60
	v_fma_f32 v11, -v33, v61, v11
	v_div_fmas_f32 v11, v11, v60, v61
	v_div_fixup_f32 v10, v11, v10, 1.0
	v_pk_mul_f32 v[58:59], v[10:11], v[58:59] op_sel_hi:[0,1]
	v_pk_mul_f32 v[10:11], v[10:11], v[12:13] op_sel_hi:[0,1]
	v_pk_mul_f32 v[12:13], v[4:5], v[10:11]
	v_pk_mul_f32 v[10:11], v[2:3], v[58:59]
	s_and_b64 vcc, exec, s[0:1]
	global_store_dwordx4 v[14:15], v[10:13], off offset:1024
	s_cbranch_vccnz .LBB0_255
	s_nop 0
	v_cvt_pk_bf16_f32 v10, v10, v11
	v_cvt_pk_bf16_f32 v11, v12, v13
	global_store_dwordx2 v[16:17], v[10:11], off offset:512

; __device__ __forceinline__ unsigned pk2(float lo, float hi) { const f32x2 v = {lo, hi}; const bf16x2_t b = __builtin_convertvector(v, bf16x2_t); return __builtin_bit_cast(unsigned, b); }
; __device__ __forceinline__ void bprep_item(Frame& F, const Args& a, int l, int item, const bf16* P, bf16* QB, bf16* KB, bf16* VT, float* QS) {
;     ...
;         for (int j = 0; j < 4; ++j) {
;             float ss = (x[j][0] * x[j][0] + x[j][1] * x[j][1]) + (x[j][2] * x[j][2] + x[j][3] * x[j][3]);
; #pragma unroll
;             for (int o = 1; o < 32; o <<= 1) ss += __shfl_xor(ss, o);
;             const float rs = 1.0f / sqrtf(ss * (1.f / 128.f) + 1e-6f);
;             if (j < 2) { const f32x4 y = x[j] * rs * qg * qs;
;                 if (!samp) *(u32x2*)(QB + (size_t)row * BW + j * 256 + 4 * lane) = (u32x2){pk2(y[0], y[1]), pk2(y[2], y[3])};
;                 else *(f32x4*)(QS + (size_t)r * BW + j * 256 + 4 * lane) = y; }
.LBB0_261:
	v_and_b32_e32 v59, 0xffff0000, v53
	v_and_b32_e32 v58, 0xffff0000, v52
	v_lshlrev_b32_e32 v13, 16, v53
	v_lshlrev_b32_e32 v12, 16, v52
	v_pk_mul_f32 v[16:17], v[58:59], v[58:59]
	s_nop 0
	v_pk_fma_f32 v[16:17], v[12:13], v[12:13], v[16:17]
	s_nop 0
	v_add_f32_e32 v16, v16, v17
	s_waitcnt lgkmcnt(0)
	s_nop 1
	v_add_f32_dpp v16, v16, v16 quad_perm:[1,0,3,2] row_mask:0xf bank_mask:0xf
	s_waitcnt lgkmcnt(0)
	s_nop 1
	v_add_f32_dpp v16, v16, v16 quad_perm:[2,3,0,1] row_mask:0xf bank_mask:0xf
	s_waitcnt lgkmcnt(0)
	s_nop 1
	v_add_f32_dpp v16, v16, v16 row_half_mirror row_mask:0xf bank_mask:0xf
	s_waitcnt lgkmcnt(0)
	s_nop 1
	v_add_f32_dpp v33, v16, v16 row_mirror row_mask:0xf bank_mask:0xf
	v_lshlrev_b64 v[16:17], 10, v[10:11]
	s_waitcnt lgkmcnt(0)
	v_mov_b32_e32 v52, v33
	v_mov_b32_e32 v10, v33
	s_nop 1
	v_permlane16_swap_b32 v52, v10
	v_add_f32_e32 v10, v10, v52
	v_fmamk_f32 v10, v10, 0x3c000000, v212
	v_mul_f32_e32 v11, 0x4f800000, v10
	v_cmp_gt_f32_e32 vcc, s67, v10
	v_lshl_add_u64 v[52:53], v[40:41], 0, v[16:17]
	s_nop 0
	v_cndmask_b32_e32 v33, v10, v11, vcc
	v_sqrt_f32_e32 v60, v33
	v_mov_b32_e32 v10, v13
	v_mov_b32_e32 v11, v59
	v_add_u32_e32 v13, -1, v60
	v_add_u32_e32 v59, 1, v60
	v_fma_f32 v61, -v13, v60, v33
	v_fma_f32 v62, -v59, v60, v33
	v_cmp_ge_f32_e64 s[4:5], 0, v61
	s_nop 1
	v_cndmask_b32_e64 v13, v60, v13, s[4:5]
	v_cmp_lt_f32_e64 s[4:5], 0, v62
	s_nop 1
	v_cndmask_b32_e64 v13, v13, v59, s[4:5]
	v_mul_f32_e32 v59, 0x37800000, v13
	v_cndmask_b32_e32 v13, v13, v59, vcc
	v_cmp_class_f32_e32 vcc, v33, v213
	s_nop 1
	v_cndmask_b32_e32 v33, v13, v33, vcc
	v_div_scale_f32 v59, s[4:5], v33, v33, 1.0
	v_rcp_f32_e32 v60, v59
	v_mov_b32_e32 v13, v58
	v_div_scale_f32 v58, vcc, 1.0, v33, 1.0
	v_fma_f32 v61, -v59, v60, 1.0
	v_fmac_f32_e32 v60, v61, v60
	v_mul_f32_e32 v61, v58, v60
	v_fma_f32 v62, -v59, v61, v58
	v_fmac_f32_e32 v61, v62, v60
	v_fma_f32 v58, -v59, v61, v58
	v_div_fmas_f32 v58, v58, v60, v61
	v_div_fixup_f32 v58, v58, v33, 1.0
	v_pk_mul_f32 v[10:11], v[58:59], v[10:11] op_sel_hi:[0,1]
	v_pk_mul_f32 v[12:13], v[58:59], v[12:13] op_sel_hi:[0,1]
	v_pk_mul_f32 v[58:59], v[6:7], v[12:13]
	v_pk_mul_f32 v[10:11], v[8:9], v[10:11]
	s_mov_b32 s4, 0x3e0293ee
	s_and_b64 vcc, exec, s[0:1]
	v_pk_mul_f32 v[12:13], v[10:11], s[4:5] op_sel_hi:[1,0]
	v_pk_mul_f32 v[10:11], v[58:59], s[4:5] op_sel_hi:[1,0]
	s_mov_b64 s[4:5], -1
	s_cbranch_vccnz .LBB0_263
	v_cvt_pk_bf16_f32 v58, v10, v11
	v_cvt_pk_bf16_f32 v59, v12, v13
	s_mov_b64 s[4:5], 0
	global_store_dwordx2 v[52:53], v[58:59], off

; __device__ __forceinline__ unsigned pk2(float lo, float hi) { const f32x2 v = {lo, hi}; const bf16x2_t b = __builtin_convertvector(v, bf16x2_t); return __builtin_bit_cast(unsigned, b); }
; __device__ __forceinline__ void bprep_item(Frame& F, const Args& a, int l, int item, const bf16* P, bf16* QB, bf16* KB, bf16* VT, float* QS) {
;     ...
;         for (int j = 0; j < 4; ++j) {
;             float ss = (x[j][0] * x[j][0] + x[j][1] * x[j][1]) + (x[j][2] * x[j][2] + x[j][3] * x[j][3]);
; #pragma unroll
;             for (int o = 1; o < 32; o <<= 1) ss += __shfl_xor(ss, o);
;             const float rs = 1.0f / sqrtf(ss * (1.f / 128.f) + 1e-6f);
;             if (j < 2) { const f32x4 y = x[j] * rs * qg * qs;
;                 if (!samp) *(u32x2*)(QB + (size_t)row * BW + j * 256 + 4 * lane) = (u32x2){pk2(y[0], y[1]), pk2(y[2], y[3])};
;                 else *(f32x4*)(QS + (size_t)r * BW + j * 256 + 4 * lane) = y; }
.LBB0_265:
	s_nop 1
	v_and_b32_e32 v13, 0xffff0000, v51
	v_and_b32_e32 v12, 0xffff0000, v50
	v_lshlrev_b32_e32 v11, 16, v51
	v_lshlrev_b32_e32 v10, 16, v50
	v_pk_mul_f32 v[50:51], v[12:13], v[12:13]
	s_nop 0
	v_pk_fma_f32 v[50:51], v[10:11], v[10:11], v[50:51]
	s_nop 0
	v_add_f32_e32 v33, v50, v51
	v_mov_b32_e32 v51, v13
	s_waitcnt lgkmcnt(0)
	s_nop 1
	v_add_f32_dpp v33, v33, v33 quad_perm:[1,0,3,2] row_mask:0xf bank_mask:0xf
	s_waitcnt lgkmcnt(0)
	s_nop 1
	v_add_f32_dpp v33, v33, v33 quad_perm:[2,3,0,1] row_mask:0xf bank_mask:0xf
	s_waitcnt lgkmcnt(0)
	s_nop 1
	v_add_f32_dpp v33, v33, v33 row_half_mirror row_mask:0xf bank_mask:0xf
	s_waitcnt lgkmcnt(0)
	s_nop 1
	v_add_f32_dpp v33, v33, v33 row_mirror row_mask:0xf bank_mask:0xf
	s_waitcnt lgkmcnt(0)
	v_mov_b32_e32 v50, v33
	s_nop 1
	v_permlane16_swap_b32 v50, v33
	v_add_f32_e32 v33, v33, v50
	v_fmamk_f32 v33, v33, 0x3c000000, v212
	v_mul_f32_e32 v50, 0x4f800000, v33
	v_cmp_gt_f32_e32 vcc, s67, v33
	s_nop 1
	v_cndmask_b32_e32 v33, v33, v50, vcc
	v_sqrt_f32_e32 v55, v33
	v_mov_b32_e32 v50, v11
	v_add_u32_e32 v11, -1, v55
	v_add_u32_e32 v13, 1, v55
	v_fma_f32 v60, -v11, v55, v33
	v_fma_f32 v61, -v13, v55, v33
	v_cmp_ge_f32_e64 s[4:5], 0, v60
	s_nop 1
	v_cndmask_b32_e64 v11, v55, v11, s[4:5]
	v_cmp_lt_f32_e64 s[4:5], 0, v61
	s_nop 1
	v_cndmask_b32_e64 v11, v11, v13, s[4:5]
	v_mul_f32_e32 v13, 0x37800000, v11
	v_cndmask_b32_e32 v11, v11, v13, vcc
	v_cmp_class_f32_e32 vcc, v33, v213
	s_nop 1
	v_cndmask_b32_e32 v13, v11, v33, vcc
	v_div_scale_f32 v33, s[4:5], v13, v13, 1.0
	v_rcp_f32_e32 v55, v33
	v_mov_b32_e32 v11, v12
	v_div_scale_f32 v12, vcc, 1.0, v13, 1.0
	v_fma_f32 v60, -v33, v55, 1.0
	v_fmac_f32_e32 v55, v60, v55
	v_mul_f32_e32 v60, v12, v55
	v_fma_f32 v61, -v33, v60, v12
	v_fmac_f32_e32 v60, v61, v55
	v_fma_f32 v12, -v33, v60, v12
	v_div_fmas_f32 v12, v12, v55, v60
	v_div_fixup_f32 v12, v12, v13, 1.0
	v_pk_mul_f32 v[50:51], v[12:13], v[50:51] op_sel_hi:[0,1]
	v_pk_mul_f32 v[10:11], v[12:13], v[10:11] op_sel_hi:[0,1]
	v_pk_mul_f32 v[10:11], v[6:7], v[10:11]
	v_pk_mul_f32 v[12:13], v[8:9], v[50:51]
	s_mov_b32 s4, 0x3e0293ee
	s_and_b64 vcc, exec, s[0:1]
	v_pk_mul_f32 v[12:13], v[12:13], s[4:5] op_sel_hi:[1,0]
	v_pk_mul_f32 v[10:11], v[10:11], s[4:5] op_sel_hi:[1,0]
	s_mov_b64 s[4:5], -1
	s_cbranch_vccnz .LBB0_267
	v_cvt_pk_bf16_f32 v50, v10, v11
	v_cvt_pk_bf16_f32 v51, v12, v13
	s_mov_b64 s[4:5], 0
	global_store_dwordx2 v[52:53], v[50:51], off offset:512

; __device__ __forceinline__ unsigned pk2(float lo, float hi) { const f32x2 v = {lo, hi}; const bf16x2_t b = __builtin_convertvector(v, bf16x2_t); return __builtin_bit_cast(unsigned, b); }
; __device__ __forceinline__ void bprep_item(Frame& F, const Args& a, int l, int item, const bf16* P, bf16* QB, bf16* KB, bf16* VT, float* QS) {
;     ...
;         for (int j = 0; j < 4; ++j) {
;             float ss = (x[j][0] * x[j][0] + x[j][1] * x[j][1]) + (x[j][2] * x[j][2] + x[j][3] * x[j][3]);
; #pragma unroll
;             for (int o = 1; o < 32; o <<= 1) ss += __shfl_xor(ss, o);
;             const float rs = 1.0f / sqrtf(ss * (1.f / 128.f) + 1e-6f);
;             if (j < 2) { const f32x4 y = x[j] * rs * qg * qs;
;                 if (!samp) *(u32x2*)(QB + (size_t)row * BW + j * 256 + 4 * lane) = (u32x2){pk2(y[0], y[1]), pk2(y[2], y[3])};
;                 else *(f32x4*)(QS + (size_t)r * BW + j * 256 + 4 * lane) = y; }
;             else { const f32x4 y = x[j] * rs * kg; *(f32x4*)(ko + (j - 2) * 256 + 4 * lane) = y;
;                 if (!samp) *(u32x2*)(KB + (size_t)row * BW + (j - 2) * 256 + 4 * lane) = (u32x2){pk2(y[0], y[1]), pk2(y[2], y[3])}; }
;         }
.LBB0_269:
	s_nop 1
	v_and_b32_e32 v13, 0xffff0000, v49
	v_and_b32_e32 v12, 0xffff0000, v48
	v_lshlrev_b32_e32 v11, 16, v49
	v_lshlrev_b32_e32 v10, 16, v48
	v_pk_mul_f32 v[48:49], v[12:13], v[12:13]
	v_lshl_add_u64 v[14:15], v[18:19], 2, v[14:15]
	v_pk_fma_f32 v[48:49], v[10:11], v[10:11], v[48:49]
	v_lshl_add_u64 v[16:17], v[36:37], 0, v[16:17]
	v_add_f32_e32 v33, v48, v49
	v_mov_b32_e32 v49, v12
	s_waitcnt lgkmcnt(0)
	s_nop 1
	v_add_f32_dpp v33, v33, v33 quad_perm:[1,0,3,2] row_mask:0xf bank_mask:0xf
	s_waitcnt lgkmcnt(0)
	s_nop 1
	v_add_f32_dpp v33, v33, v33 quad_perm:[2,3,0,1] row_mask:0xf bank_mask:0xf
	s_waitcnt lgkmcnt(0)
	s_nop 1
	v_add_f32_dpp v33, v33, v33 row_half_mirror row_mask:0xf bank_mask:0xf
	s_waitcnt lgkmcnt(0)
	s_nop 1
	v_add_f32_dpp v33, v33, v33 row_mirror row_mask:0xf bank_mask:0xf
	s_waitcnt lgkmcnt(0)
	v_mov_b32_e32 v48, v33
	s_nop 1
	v_permlane16_swap_b32 v48, v33
	v_add_f32_e32 v33, v33, v48
	v_fmamk_f32 v33, v33, 0x3c000000, v212
	v_mul_f32_e32 v48, 0x4f800000, v33
	v_cmp_gt_f32_e32 vcc, s67, v33
	s_nop 1
	v_cndmask_b32_e32 v33, v33, v48, vcc
	v_sqrt_f32_e32 v50, v33
	v_mov_b32_e32 v48, v10
	v_add_u32_e32 v10, -1, v50
	v_add_u32_e32 v12, 1, v50
	v_fma_f32 v51, -v10, v50, v33
	v_fma_f32 v52, -v12, v50, v33
	v_cmp_ge_f32_e64 s[4:5], 0, v51
	s_nop 1
	v_cndmask_b32_e64 v10, v50, v10, s[4:5]
	v_cmp_lt_f32_e64 s[4:5], 0, v52
	s_nop 1
	v_cndmask_b32_e64 v10, v10, v12, s[4:5]
	v_mul_f32_e32 v12, 0x37800000, v10
	v_cndmask_b32_e32 v10, v10, v12, vcc
	v_cmp_class_f32_e32 vcc, v33, v213
	v_mov_b32_e32 v12, v11
	s_nop 0
	v_cndmask_b32_e32 v10, v10, v33, vcc
	v_div_scale_f32 v33, s[4:5], v10, v10, 1.0
	v_rcp_f32_e32 v50, v33
	v_div_scale_f32 v11, vcc, 1.0, v10, 1.0
	v_fma_f32 v51, -v33, v50, 1.0
	v_fmac_f32_e32 v50, v51, v50
	v_mul_f32_e32 v51, v11, v50
	v_fma_f32 v52, -v33, v51, v11
	v_fmac_f32_e32 v51, v52, v50
	v_fma_f32 v11, -v33, v51, v11
	v_div_fmas_f32 v11, v11, v50, v51
	v_div_fixup_f32 v10, v11, v10, 1.0
	v_pk_mul_f32 v[48:49], v[10:11], v[48:49] op_sel_hi:[0,1]
	v_pk_mul_f32 v[10:11], v[10:11], v[12:13] op_sel_hi:[0,1]
	v_pk_mul_f32 v[12:13], v[4:5], v[10:11]
	v_pk_mul_f32 v[10:11], v[2:3], v[48:49]
	s_and_b64 vcc, exec, s[0:1]
	global_store_dwordx4 v[14:15], v[10:13], off
	s_cbranch_vccnz .LBB0_271
	s_nop 0
	v_cvt_pk_bf16_f32 v10, v10, v11
	v_cvt_pk_bf16_f32 v11, v12, v13
	global_store_dwordx2 v[16:17], v[10:11], off
.LBB0_271:
	s_nop 0
	v_and_b32_e32 v13, 0xffff0000, v47
	v_and_b32_e32 v12, 0xffff0000, v46
	v_lshlrev_b32_e32 v11, 16, v47
	v_lshlrev_b32_e32 v10, 16, v46
	v_pk_mul_f32 v[46:47], v[12:13], v[12:13]
	s_nop 0
	v_pk_fma_f32 v[46:47], v[10:11], v[10:11], v[46:47]
	s_nop 0
	v_add_f32_e32 v33, v46, v47
	v_mov_b32_e32 v47, v12
	s_waitcnt lgkmcnt(0)
	s_nop 1
	v_add_f32_dpp v33, v33, v33 quad_perm:[1,0,3,2] row_mask:0xf bank_mask:0xf
	s_waitcnt lgkmcnt(0)
	s_nop 1
	v_add_f32_dpp v33, v33, v33 quad_perm:[2,3,0,1] row_mask:0xf bank_mask:0xf
	s_waitcnt lgkmcnt(0)
	s_nop 1
	v_add_f32_dpp v33, v33, v33 row_half_mirror row_mask:0xf bank_mask:0xf
	s_waitcnt lgkmcnt(0)
	s_nop 1
	v_add_f32_dpp v33, v33, v33 row_mirror row_mask:0xf bank_mask:0xf
	s_waitcnt lgkmcnt(0)
	v_mov_b32_e32 v46, v33
	s_nop 1
	v_permlane16_swap_b32 v46, v33
	v_add_f32_e32 v33, v33, v46
	v_fmamk_f32 v33, v33, 0x3c000000, v212
	v_mul_f32_e32 v46, 0x4f800000, v33
	v_cmp_gt_f32_e32 vcc, s67, v33
	s_nop 1
	v_cndmask_b32_e32 v33, v33, v46, vcc
	v_sqrt_f32_e32 v48, v33
	v_mov_b32_e32 v46, v10
	v_add_u32_e32 v10, -1, v48
	v_add_u32_e32 v12, 1, v48
	v_fma_f32 v49, -v10, v48, v33
	v_fma_f32 v50, -v12, v48, v33
	v_cmp_ge_f32_e64 s[4:5], 0, v49
	s_nop 1
	v_cndmask_b32_e64 v10, v48, v10, s[4:5]
	v_cmp_lt_f32_e64 s[4:5], 0, v50
	s_nop 1
	v_cndmask_b32_e64 v10, v10, v12, s[4:5]
	v_mul_f32_e32 v12, 0x37800000, v10
	v_cndmask_b32_e32 v10, v10, v12, vcc
	v_cmp_class_f32_e32 vcc, v33, v213
	v_mov_b32_e32 v12, v11
	s_nop 0
	v_cndmask_b32_e32 v10, v10, v33, vcc
	v_div_scale_f32 v33, s[4:5], v10, v10, 1.0
	v_rcp_f32_e32 v48, v33
	v_div_scale_f32 v11, vcc, 1.0, v10, 1.0
	v_fma_f32 v49, -v33, v48, 1.0
	v_fmac_f32_e32 v48, v49, v48
	v_mul_f32_e32 v49, v11, v48
	v_fma_f32 v50, -v33, v49, v11
	v_fmac_f32_e32 v49, v50, v48
	v_fma_f32 v11, -v33, v49, v11
	v_div_fmas_f32 v11, v11, v48, v49
	v_div_fixup_f32 v10, v11, v10, 1.0
	v_pk_mul_f32 v[46:47], v[10:11], v[46:47] op_sel_hi:[0,1]
	v_pk_mul_f32 v[10:11], v[10:11], v[12:13] op_sel_hi:[0,1]
	v_pk_mul_f32 v[12:13], v[4:5], v[10:11]
	v_pk_mul_f32 v[10:11], v[2:3], v[46:47]
	s_and_b64 vcc, exec, s[0:1]
	global_store_dwordx4 v[14:15], v[10:13], off offset:1024
	s_cbranch_vccnz .LBB0_273
	s_nop 0
	v_cvt_pk_bf16_f32 v10, v10, v11
	v_cvt_pk_bf16_f32 v11, v12, v13
	global_store_dwordx2 v[16:17], v[10:11], off offset:512

; __device__ __forceinline__ unsigned pk2(float lo, float hi) { const f32x2 v = {lo, hi}; const bf16x2_t b = __builtin_convertvector(v, bf16x2_t); return __builtin_bit_cast(unsigned, b); }
; __device__ __forceinline__ void bprep_item(Frame& F, const Args& a, int l, int item, const bf16* P, bf16* QB, bf16* KB, bf16* VT, float* QS) {
;     ...
;         for (int j = 0; j < 4; ++j) {
;             float ss = (x[j][0] * x[j][0] + x[j][1] * x[j][1]) + (x[j][2] * x[j][2] + x[j][3] * x[j][3]);
; #pragma unroll
;             for (int o = 1; o < 32; o <<= 1) ss += __shfl_xor(ss, o);
;             const float rs = 1.0f / sqrtf(ss * (1.f / 128.f) + 1e-6f);
;             if (j < 2) { const f32x4 y = x[j] * rs * qg * qs;
;                 if (!samp) *(u32x2*)(QB + (size_t)row * BW + j * 256 + 4 * lane) = (u32x2){pk2(y[0], y[1]), pk2(y[2], y[3])};
;                 else *(f32x4*)(QS + (size_t)r * BW + j * 256 + 4 * lane) = y; }
.LBB0_279:
	v_and_b32_e32 v43, 0xffff0000, v31
	v_and_b32_e32 v42, 0xffff0000, v30
	v_lshlrev_b32_e32 v13, 16, v31
	v_lshlrev_b32_e32 v12, 16, v30
	v_pk_mul_f32 v[30:31], v[42:43], v[42:43]
	s_nop 0
	v_pk_fma_f32 v[30:31], v[12:13], v[12:13], v[30:31]
	s_nop 0
	v_add_f32_e32 v30, v30, v31
	s_waitcnt lgkmcnt(0)
	s_nop 1
	v_add_f32_dpp v30, v30, v30 quad_perm:[1,0,3,2] row_mask:0xf bank_mask:0xf
	s_waitcnt lgkmcnt(0)
	s_nop 1
	v_add_f32_dpp v30, v30, v30 quad_perm:[2,3,0,1] row_mask:0xf bank_mask:0xf
	s_waitcnt lgkmcnt(0)
	s_nop 1
	v_add_f32_dpp v30, v30, v30 row_half_mirror row_mask:0xf bank_mask:0xf
	s_waitcnt lgkmcnt(0)
	s_nop 1
	v_add_f32_dpp v44, v30, v30 row_mirror row_mask:0xf bank_mask:0xf
	v_lshlrev_b64 v[30:31], 10, v[10:11]
	v_lshl_add_u64 v[40:41], v[40:41], 0, v[30:31]
	s_waitcnt lgkmcnt(0)
	v_mov_b32_e32 v45, v44
	v_mov_b32_e32 v10, v44
	s_nop 1
	v_permlane16_swap_b32 v45, v10
	v_add_f32_e32 v10, v10, v45
	v_fmamk_f32 v10, v10, 0x3c000000, v212
	v_mul_f32_e32 v11, 0x4f800000, v10
	v_cmp_gt_f32_e32 vcc, s67, v10
	s_nop 1
	v_cndmask_b32_e32 v44, v10, v11, vcc
	v_sqrt_f32_e32 v45, v44
	v_mov_b32_e32 v10, v13
	v_mov_b32_e32 v11, v43
	v_add_u32_e32 v13, -1, v45
	v_add_u32_e32 v43, 1, v45
	v_fma_f32 v46, -v13, v45, v44
	v_fma_f32 v47, -v43, v45, v44
	v_cmp_ge_f32_e64 s[4:5], 0, v46
	s_nop 1
	v_cndmask_b32_e64 v13, v45, v13, s[4:5]
	v_cmp_lt_f32_e64 s[4:5], 0, v47
	s_nop 1
	v_cndmask_b32_e64 v13, v13, v43, s[4:5]
	v_mul_f32_e32 v43, 0x37800000, v13
	v_cndmask_b32_e32 v13, v13, v43, vcc
	v_cmp_class_f32_e32 vcc, v44, v213
	s_nop 1
	v_cndmask_b32_e32 v43, v13, v44, vcc
	v_div_scale_f32 v44, s[2:3], v43, v43, 1.0
	v_rcp_f32_e32 v45, v44
	v_mov_b32_e32 v13, v42
	v_div_scale_f32 v42, vcc, 1.0, v43, 1.0
	v_fma_f32 v46, -v44, v45, 1.0
	v_fmac_f32_e32 v45, v46, v45
	v_mul_f32_e32 v46, v42, v45
	v_fma_f32 v47, -v44, v46, v42
	v_fmac_f32_e32 v46, v47, v45
	v_fma_f32 v42, -v44, v46, v42
	v_div_fmas_f32 v42, v42, v45, v46
	v_div_fixup_f32 v42, v42, v43, 1.0
	v_pk_mul_f32 v[10:11], v[42:43], v[10:11] op_sel_hi:[0,1]
	v_pk_mul_f32 v[12:13], v[42:43], v[12:13] op_sel_hi:[0,1]
	v_pk_mul_f32 v[42:43], v[6:7], v[12:13]
	v_pk_mul_f32 v[10:11], v[8:9], v[10:11]
	s_mov_b32 s2, 0x3e0293ee
	s_and_b64 vcc, exec, s[0:1]
	v_pk_mul_f32 v[12:13], v[10:11], s[2:3] op_sel_hi:[1,0]
	v_pk_mul_f32 v[10:11], v[42:43], s[2:3] op_sel_hi:[1,0]
	s_mov_b64 s[2:3], -1
	s_cbranch_vccnz .LBB0_281
	v_cvt_pk_bf16_f32 v42, v10, v11
	v_cvt_pk_bf16_f32 v43, v12, v13
	s_mov_b64 s[2:3], 0
	global_store_dwordx2 v[40:41], v[42:43], off

; __device__ __forceinline__ unsigned pk2(float lo, float hi) { const f32x2 v = {lo, hi}; const bf16x2_t b = __builtin_convertvector(v, bf16x2_t); return __builtin_bit_cast(unsigned, b); }
; __device__ __forceinline__ void bprep_item(Frame& F, const Args& a, int l, int item, const bf16* P, bf16* QB, bf16* KB, bf16* VT, float* QS) {
;     ...
;         for (int j = 0; j < 4; ++j) {
;             float ss = (x[j][0] * x[j][0] + x[j][1] * x[j][1]) + (x[j][2] * x[j][2] + x[j][3] * x[j][3]);
; #pragma unroll
;             for (int o = 1; o < 32; o <<= 1) ss += __shfl_xor(ss, o);
;             const float rs = 1.0f / sqrtf(ss * (1.f / 128.f) + 1e-6f);
;             if (j < 2) { const f32x4 y = x[j] * rs * qg * qs;
;                 if (!samp) *(u32x2*)(QB + (size_t)row * BW + j * 256 + 4 * lane) = (u32x2){pk2(y[0], y[1]), pk2(y[2], y[3])};
;                 else *(f32x4*)(QS + (size_t)r * BW + j * 256 + 4 * lane) = y; }
.LBB0_283:
	s_nop 1
	v_and_b32_e32 v13, 0xffff0000, v29
	v_and_b32_e32 v12, 0xffff0000, v28
	v_lshlrev_b32_e32 v11, 16, v29
	v_lshlrev_b32_e32 v10, 16, v28
	v_pk_mul_f32 v[28:29], v[12:13], v[12:13]
	s_nop 0
	v_pk_fma_f32 v[28:29], v[10:11], v[10:11], v[28:29]
	s_nop 0
	v_add_f32_e32 v15, v28, v29
	v_mov_b32_e32 v29, v13
	s_waitcnt lgkmcnt(0)
	s_nop 1
	v_add_f32_dpp v15, v15, v15 quad_perm:[1,0,3,2] row_mask:0xf bank_mask:0xf
	s_waitcnt lgkmcnt(0)
	s_nop 1
	v_add_f32_dpp v15, v15, v15 quad_perm:[2,3,0,1] row_mask:0xf bank_mask:0xf
	s_waitcnt lgkmcnt(0)
	s_nop 1
	v_add_f32_dpp v15, v15, v15 row_half_mirror row_mask:0xf bank_mask:0xf
	s_waitcnt lgkmcnt(0)
	s_nop 1
	v_add_f32_dpp v15, v15, v15 row_mirror row_mask:0xf bank_mask:0xf
	s_waitcnt lgkmcnt(0)
	v_mov_b32_e32 v28, v15
	s_nop 1
	v_permlane16_swap_b32 v28, v15
	v_add_f32_e32 v15, v15, v28
	v_fmamk_f32 v15, v15, 0x3c000000, v212
	v_mul_f32_e32 v28, 0x4f800000, v15
	v_cmp_gt_f32_e32 vcc, s67, v15
	s_nop 1
	v_cndmask_b32_e32 v15, v15, v28, vcc
	v_sqrt_f32_e32 v42, v15
	v_mov_b32_e32 v28, v11
	v_add_u32_e32 v11, -1, v42
	v_add_u32_e32 v13, 1, v42
	v_fma_f32 v43, -v11, v42, v15
	v_fma_f32 v44, -v13, v42, v15
	v_cmp_ge_f32_e64 s[4:5], 0, v43
	s_nop 1
	v_cndmask_b32_e64 v11, v42, v11, s[4:5]
	v_cmp_lt_f32_e64 s[4:5], 0, v44
	s_nop 1
	v_cndmask_b32_e64 v11, v11, v13, s[4:5]
	v_mul_f32_e32 v13, 0x37800000, v11
	v_cndmask_b32_e32 v11, v11, v13, vcc
	v_cmp_class_f32_e32 vcc, v15, v213
	s_nop 1
	v_cndmask_b32_e32 v13, v11, v15, vcc
	v_div_scale_f32 v15, s[2:3], v13, v13, 1.0
	v_rcp_f32_e32 v42, v15
	v_mov_b32_e32 v11, v12
	v_div_scale_f32 v12, vcc, 1.0, v13, 1.0
	v_fma_f32 v43, -v15, v42, 1.0
	v_fmac_f32_e32 v42, v43, v42
	v_mul_f32_e32 v43, v12, v42
	v_fma_f32 v44, -v15, v43, v12
	v_fmac_f32_e32 v43, v44, v42
	v_fma_f32 v12, -v15, v43, v12
	v_div_fmas_f32 v12, v12, v42, v43
	v_div_fixup_f32 v12, v12, v13, 1.0
	v_pk_mul_f32 v[28:29], v[12:13], v[28:29] op_sel_hi:[0,1]
	v_pk_mul_f32 v[10:11], v[12:13], v[10:11] op_sel_hi:[0,1]
	v_pk_mul_f32 v[6:7], v[6:7], v[10:11]
	v_pk_mul_f32 v[8:9], v[8:9], v[28:29]
	s_mov_b32 s2, 0x3e0293ee
	s_and_b64 vcc, exec, s[0:1]
	v_pk_mul_f32 v[8:9], v[8:9], s[2:3] op_sel_hi:[1,0]
	v_pk_mul_f32 v[6:7], v[6:7], s[2:3] op_sel_hi:[1,0]
	s_mov_b64 s[2:3], -1
	s_cbranch_vccnz .LBB0_285
	v_cvt_pk_bf16_f32 v10, v6, v7
	v_cvt_pk_bf16_f32 v11, v8, v9
	s_mov_b64 s[2:3], 0
	global_store_dwordx2 v[40:41], v[10:11], off offset:512

; __device__ __forceinline__ unsigned pk2(float lo, float hi) { const f32x2 v = {lo, hi}; const bf16x2_t b = __builtin_convertvector(v, bf16x2_t); return __builtin_bit_cast(unsigned, b); }
; __device__ __forceinline__ void bprep_item(Frame& F, const Args& a, int l, int item, const bf16* P, bf16* QB, bf16* KB, bf16* VT, float* QS) {
;     ...
;         for (int j = 0; j < 4; ++j) {
;             float ss = (x[j][0] * x[j][0] + x[j][1] * x[j][1]) + (x[j][2] * x[j][2] + x[j][3] * x[j][3]);
; #pragma unroll
;             for (int o = 1; o < 32; o <<= 1) ss += __shfl_xor(ss, o);
;             const float rs = 1.0f / sqrtf(ss * (1.f / 128.f) + 1e-6f);
;             if (j < 2) { const f32x4 y = x[j] * rs * qg * qs;
;                 if (!samp) *(u32x2*)(QB + (size_t)row * BW + j * 256 + 4 * lane) = (u32x2){pk2(y[0], y[1]), pk2(y[2], y[3])};
;                 else *(f32x4*)(QS + (size_t)r * BW + j * 256 + 4 * lane) = y; }
;             else { const f32x4 y = x[j] * rs * kg; *(f32x4*)(ko + (j - 2) * 256 + 4 * lane) = y;
;                 if (!samp) *(u32x2*)(KB + (size_t)row * BW + (j - 2) * 256 + 4 * lane) = (u32x2){pk2(y[0], y[1]), pk2(y[2], y[3])}; }
;         }
.LBB0_287:
	s_nop 1
	v_and_b32_e32 v9, 0xffff0000, v27
	v_and_b32_e32 v8, 0xffff0000, v26
	v_lshlrev_b32_e32 v7, 16, v27
	v_lshlrev_b32_e32 v6, 16, v26
	v_pk_mul_f32 v[10:11], v[8:9], v[8:9]
	v_mov_b32_e32 v26, v6
	v_pk_fma_f32 v[10:11], v[6:7], v[6:7], v[10:11]
	v_mov_b32_e32 v27, v8
	v_add_f32_e32 v10, v10, v11
	s_waitcnt lgkmcnt(0)
	s_nop 1
	v_add_f32_dpp v10, v10, v10 quad_perm:[1,0,3,2] row_mask:0xf bank_mask:0xf
	s_waitcnt lgkmcnt(0)
	s_nop 1
	v_add_f32_dpp v10, v10, v10 quad_perm:[2,3,0,1] row_mask:0xf bank_mask:0xf
	s_waitcnt lgkmcnt(0)
	s_nop 1
	v_add_f32_dpp v10, v10, v10 row_half_mirror row_mask:0xf bank_mask:0xf
	s_waitcnt lgkmcnt(0)
	s_nop 1
	v_add_f32_dpp v12, v10, v10 row_mirror row_mask:0xf bank_mask:0xf
	v_lshl_add_u64 v[10:11], v[18:19], 2, v[32:33]
	s_waitcnt lgkmcnt(0)
	v_mov_b32_e32 v13, v12
	s_nop 1
	v_permlane16_swap_b32 v13, v12
	v_add_f32_e32 v12, v12, v13
	v_fmamk_f32 v12, v12, 0x3c000000, v212
	v_mul_f32_e32 v13, 0x4f800000, v12
	v_cmp_gt_f32_e32 vcc, s67, v12
	s_nop 1
	v_cndmask_b32_e32 v15, v12, v13, vcc
	v_sqrt_f32_e32 v28, v15
	v_lshl_add_u64 v[12:13], v[36:37], 0, v[30:31]
	v_add_u32_e32 v6, -1, v28
	v_add_u32_e32 v8, 1, v28
	v_fma_f32 v29, -v6, v28, v15
	v_fma_f32 v30, -v8, v28, v15
	v_cmp_ge_f32_e64 s[4:5], 0, v29
	s_nop 1
	v_cndmask_b32_e64 v6, v28, v6, s[4:5]
	v_cmp_lt_f32_e64 s[4:5], 0, v30
	s_nop 1
	v_cndmask_b32_e64 v6, v6, v8, s[4:5]
	v_mul_f32_e32 v8, 0x37800000, v6
	v_cndmask_b32_e32 v6, v6, v8, vcc
	v_cmp_class_f32_e32 vcc, v15, v213
	v_mov_b32_e32 v8, v7
	s_nop 0
	v_cndmask_b32_e32 v6, v6, v15, vcc
	v_div_scale_f32 v15, s[2:3], v6, v6, 1.0
	v_rcp_f32_e32 v28, v15
	v_div_scale_f32 v7, vcc, 1.0, v6, 1.0
	v_fma_f32 v29, -v15, v28, 1.0
	v_fmac_f32_e32 v28, v29, v28
	v_mul_f32_e32 v29, v7, v28
	v_fma_f32 v30, -v15, v29, v7
	v_fmac_f32_e32 v29, v30, v28
	v_fma_f32 v7, -v15, v29, v7
	v_div_fmas_f32 v7, v7, v28, v29
	v_div_fixup_f32 v6, v7, v6, 1.0
	v_pk_mul_f32 v[26:27], v[6:7], v[26:27] op_sel_hi:[0,1]
	v_pk_mul_f32 v[6:7], v[6:7], v[8:9] op_sel_hi:[0,1]
	v_pk_mul_f32 v[8:9], v[4:5], v[6:7]
	v_pk_mul_f32 v[6:7], v[2:3], v[26:27]
	s_and_b64 vcc, exec, s[0:1]
	global_store_dwordx4 v[10:11], v[6:9], off
	s_cbranch_vccnz .LBB0_289
	s_nop 0
	v_cvt_pk_bf16_f32 v6, v6, v7
	v_cvt_pk_bf16_f32 v7, v8, v9
	global_store_dwordx2 v[12:13], v[6:7], off
.LBB0_289:
	s_nop 0
	v_and_b32_e32 v9, 0xffff0000, v25
	v_and_b32_e32 v8, 0xffff0000, v24
	v_lshlrev_b32_e32 v7, 16, v25
	v_lshlrev_b32_e32 v6, 16, v24
	v_pk_mul_f32 v[24:25], v[8:9], v[8:9]
	s_nop 0
	v_pk_fma_f32 v[24:25], v[6:7], v[6:7], v[24:25]
	s_nop 0
	v_add_f32_e32 v15, v24, v25
	v_mov_b32_e32 v25, v8
	s_waitcnt lgkmcnt(0)
	s_nop 1
	v_add_f32_dpp v15, v15, v15 quad_perm:[1,0,3,2] row_mask:0xf bank_mask:0xf
	s_waitcnt lgkmcnt(0)
	s_nop 1
	v_add_f32_dpp v15, v15, v15 quad_perm:[2,3,0,1] row_mask:0xf bank_mask:0xf
	s_waitcnt lgkmcnt(0)
	s_nop 1
	v_add_f32_dpp v15, v15, v15 row_half_mirror row_mask:0xf bank_mask:0xf
	s_waitcnt lgkmcnt(0)
	s_nop 1
	v_add_f32_dpp v15, v15, v15 row_mirror row_mask:0xf bank_mask:0xf
	s_waitcnt lgkmcnt(0)
	v_mov_b32_e32 v24, v15
	s_nop 1
	v_permlane16_swap_b32 v24, v15
	v_add_f32_e32 v15, v15, v24
	v_fmamk_f32 v15, v15, 0x3c000000, v212
	v_mul_f32_e32 v24, 0x4f800000, v15
	v_cmp_gt_f32_e32 vcc, s67, v15
	s_nop 1
	v_cndmask_b32_e32 v15, v15, v24, vcc
	v_sqrt_f32_e32 v26, v15
	v_mov_b32_e32 v24, v6
	v_add_u32_e32 v6, -1, v26
	v_add_u32_e32 v8, 1, v26
	v_fma_f32 v27, -v6, v26, v15
	v_fma_f32 v28, -v8, v26, v15
	v_cmp_ge_f32_e64 s[4:5], 0, v27
	s_nop 1
	v_cndmask_b32_e64 v6, v26, v6, s[4:5]
	v_cmp_lt_f32_e64 s[4:5], 0, v28
	s_nop 1
	v_cndmask_b32_e64 v6, v6, v8, s[4:5]
	v_mul_f32_e32 v8, 0x37800000, v6
	v_cndmask_b32_e32 v6, v6, v8, vcc
	v_cmp_class_f32_e32 vcc, v15, v213
	v_mov_b32_e32 v8, v7
	s_nop 0
	v_cndmask_b32_e32 v6, v6, v15, vcc
	v_div_scale_f32 v15, s[2:3], v6, v6, 1.0
	v_rcp_f32_e32 v26, v15
	v_div_scale_f32 v7, vcc, 1.0, v6, 1.0
	v_fma_f32 v27, -v15, v26, 1.0
	v_fmac_f32_e32 v26, v27, v26
	v_mul_f32_e32 v27, v7, v26
	v_fma_f32 v28, -v15, v27, v7
	v_fmac_f32_e32 v27, v28, v26
	v_fma_f32 v7, -v15, v27, v7
	v_div_fmas_f32 v7, v7, v26, v27
	v_div_fixup_f32 v6, v7, v6, 1.0
	v_pk_mul_f32 v[24:25], v[6:7], v[24:25] op_sel_hi:[0,1]
	v_pk_mul_f32 v[6:7], v[6:7], v[8:9] op_sel_hi:[0,1]
	v_pk_mul_f32 v[4:5], v[4:5], v[6:7]
	v_pk_mul_f32 v[2:3], v[2:3], v[24:25]
	s_and_b64 vcc, exec, s[0:1]
	global_store_dwordx4 v[10:11], v[2:5], off offset:1024
	s_cbranch_vccnz .LBB0_291
	s_nop 0
	v_cvt_pk_bf16_f32 v2, v2, v3
	v_cvt_pk_bf16_f32 v3, v4, v5
	global_store_dwordx2 v[12:13], v[2:3], off offset:512

; __device__ __forceinline__ float ex2(float x) { return __builtin_amdgcn_exp2f(x); }
; __device__ __forceinline__ float rcpf_(float x) { return __builtin_amdgcn_rcpf(x); }
; __device__ __forceinline__ f32x4 ldb4(const bf16* p) { const u32x2 w = *(const u32x2*)p; return (f32x4){__builtin_bit_cast(float, w.x << 16), __builtin_bit_cast(float, w.x & 0xffff0000u), __builtin_bit_cast(float, w.y << 16), __builtin_bit_cast(float, w.y & 0xffff0000u)}; }
; __device__ __forceinline__ float gelu_tanh(float x) {
;     const float u = 0.7978845608028654f * (x + 0.044715f * x * x * x);
;     const float t = 1.0f - 2.0f * rcpf_(1.0f + ex2(2.0f * LOG2E * u));
;     return 0.5f * x * (1.0f + t);
; }
; __device__ __forceinline__ void gmlp_item(Frame& F, const Args& a, int l, int chunk, int g, const bf16* P, bf16* ACTA) {
;     ...
;         for (int i = 0; i < 8; ++i) { const bf16* pr = P + (size_t)(row0 + w * 16 + i0 + i) * NPRE + PA0 + 512; xa[i] = ldb4(pr + 4 * lane); xb[i] = ldb4(pr + 256 + 4 * lane); }
; #pragma unroll
;         for (int i = 0; i < 8; ++i) {
;             const int s = w * 16 + i0 + i; f32x4 x0 = xa[i], x1 = xb[i];
; #pragma unroll
;             for (int j = 0; j < 4; ++j) { x0[j] = gelu_tanh(x0[j]); x1[j] = gelu_tanh(x1[j]); }
;             const float mean = wave_sum((x0[0] + x0[1]) + (x0[2] + x0[3]) + (x1[0] + x1[1]) + (x1[2] + x1[3])) * (1.f / 512.f);
.LBB0_543:
	v_or_b32_e32 v62, s2, v34
	v_mad_i64_i32 v[12:13], s[4:5], v62, s68, v[10:11]
	global_load_dwordx2 v[14:15], v[12:13], off offset:1024
	s_nop 0
	global_load_dwordx2 v[12:13], v[12:13], off offset:1536
	v_or_b32_e32 v16, 1, v62
	v_or_b32_e32 v20, 3, v62
	v_or_b32_e32 v22, 4, v62
	v_or_b32_e32 v18, 2, v62
	v_or_b32_e32 v24, 5, v62
	v_mad_i64_i32 v[16:17], s[4:5], v16, s68, v[10:11]
	s_waitcnt lgkmcnt(0)
	v_mad_i64_i32 v[20:21], s[4:5], v20, s68, v[10:11]
	v_mad_i64_i32 v[22:23], s[4:5], v22, s68, v[10:11]
	v_mad_i64_i32 v[18:19], s[4:5], v18, s68, v[10:11]
	v_mad_i64_i32 v[42:43], s[4:5], v24, s68, v[10:11]
	global_load_dwordx2 v[40:41], v[16:17], off offset:1024
	global_load_dwordx2 v[38:39], v[16:17], off offset:1536
	global_load_dwordx2 v[36:37], v[18:19], off offset:1024
	global_load_dwordx2 v[32:33], v[18:19], off offset:1536
	global_load_dwordx2 v[30:31], v[20:21], off offset:1024
	global_load_dwordx2 v[28:29], v[20:21], off offset:1536
	global_load_dwordx2 v[26:27], v[22:23], off offset:1024
	global_load_dwordx2 v[24:25], v[22:23], off offset:1536
	s_nop 0
	global_load_dwordx2 v[22:23], v[42:43], off offset:1024
	global_load_dwordx2 v[20:21], v[42:43], off offset:1536
	v_or_b32_e32 v63, 6, v62
	s_waitcnt vmcnt(0)
	v_lshlrev_b32_e32 v16, 16, v14
	v_and_b32_e32 v17, 0xffff0000, v14
	v_mul_f32_e32 v46, 0x3d372713, v16
	v_mul_f32_e32 v48, 0x3d372713, v17
	v_mov_b32_e32 v47, v16
	v_mov_b32_e32 v49, v17
	v_pk_mul_f32 v[42:43], v[16:17], 0.5 op_sel_hi:[1,0]
	v_mul_f32_e32 v16, v46, v16
	v_mul_f32_e32 v17, v48, v17
	v_fmac_f32_e32 v47, v16, v47
	v_fmac_f32_e32 v49, v17, v49
	v_mul_f32_e32 v16, 0x3f4c422a, v47
	v_mul_f32_e32 v17, 0x3f4c422a, v49
	v_lshlrev_b32_e32 v18, 16, v12
	v_and_b32_e32 v19, 0xffff0000, v12
	v_mul_f32_e32 v16, 0x4038aa3b, v16
	v_mul_f32_e32 v17, 0x4038aa3b, v17
	v_mul_f32_e32 v64, 0x3d372713, v18
	v_mul_f32_e32 v66, 0x3d372713, v19
	v_exp_f32_e32 v16, v16
	v_exp_f32_e32 v17, v17
	v_mov_b32_e32 v65, v18
	v_mov_b32_e32 v67, v19
	v_pk_mul_f32 v[44:45], v[18:19], 0.5 op_sel_hi:[1,0]
	v_mul_f32_e32 v18, v64, v18
	v_mul_f32_e32 v19, v66, v19
	v_fmac_f32_e32 v65, v18, v65
	v_fmac_f32_e32 v67, v19, v67
	v_mul_f32_e32 v18, 0x3f4c422a, v65
	v_mul_f32_e32 v19, 0x3f4c422a, v67
	v_mul_f32_e32 v18, 0x4038aa3b, v18
	v_mul_f32_e32 v19, 0x4038aa3b, v19
	v_add_f32_e32 v16, 1.0, v16
	v_add_f32_e32 v17, 1.0, v17
	v_exp_f32_e32 v18, v18
	v_exp_f32_e32 v19, v19
	v_rcp_f32_e32 v16, v16
	v_rcp_f32_e32 v17, v17
	v_add_f32_e32 v18, 1.0, v18
	v_add_f32_e32 v19, 1.0, v19
	v_lshlrev_b32_e32 v12, 16, v13
	v_pk_fma_f32 v[16:17], v[16:17], 2.0, 1.0 op_sel_hi:[1,0,0] neg_lo:[1,0,0] neg_hi:[1,0,0]
	v_rcp_f32_e32 v18, v18
	v_rcp_f32_e32 v19, v19
	v_pk_add_f32 v[16:17], v[16:17], 1.0 op_sel_hi:[1,0]
	v_lshlrev_b32_e32 v14, 16, v15
	v_pk_mul_f32 v[42:43], v[42:43], v[16:17]
	v_mul_f32_e32 v16, 0x3d372713, v12
	v_mul_f32_e32 v16, v16, v12
	v_mov_b32_e32 v17, v12
	v_and_b32_e32 v15, 0xffff0000, v15
	v_fmac_f32_e32 v17, v16, v17
	v_mul_f32_e32 v68, 0x3d372713, v14
	v_mul_f32_e32 v70, 0x3d372713, v15
	v_pk_fma_f32 v[18:19], v[18:19], 2.0, 1.0 op_sel_hi:[1,0,0] neg_lo:[1,0,0] neg_hi:[1,0,0]
	v_mul_f32_e32 v16, 0x3f4c422a, v17
	v_mov_b32_e32 v69, v14
	v_mov_b32_e32 v71, v15
	v_mul_f32_e32 v46, v68, v14
	v_mul_f32_e32 v48, v70, v15
	v_pk_add_f32 v[18:19], v[18:19], 1.0 op_sel_hi:[1,0]
	v_and_b32_e32 v13, 0xffff0000, v13
	v_mul_f32_e32 v16, 0x4038aa3b, v16
	v_fmac_f32_e32 v69, v46, v69
	v_fmac_f32_e32 v71, v48, v71
	v_pk_mul_f32 v[44:45], v[44:45], v[18:19]
	v_exp_f32_e32 v18, v16
	v_mul_f32_e32 v16, 0x3d372713, v13
	v_mul_f32_e32 v46, 0x3f4c422a, v69
	v_mul_f32_e32 v47, 0x3f4c422a, v71
	v_mul_f32_e32 v16, v16, v13
	v_mov_b32_e32 v17, v13
	v_mul_f32_e32 v46, 0x4038aa3b, v46
	v_mul_f32_e32 v47, 0x4038aa3b, v47
	v_fmac_f32_e32 v17, v16, v17
	v_exp_f32_e32 v46, v46
	v_exp_f32_e32 v47, v47
	v_mul_f32_e32 v16, 0x3f4c422a, v17
	v_mul_f32_e32 v16, 0x4038aa3b, v16
	v_exp_f32_e32 v19, v16
	v_add_f32_e32 v46, 1.0, v46
	v_add_f32_e32 v47, 1.0, v47
	v_rcp_f32_e32 v46, v46
	v_rcp_f32_e32 v47, v47
	v_add_f32_e32 v18, 1.0, v18
	v_add_f32_e32 v19, 1.0, v19
	v_rcp_f32_e32 v18, v18
	v_rcp_f32_e32 v19, v19
	v_pk_fma_f32 v[16:17], v[46:47], 2.0, 1.0 op_sel_hi:[1,0,0] neg_lo:[1,0,0] neg_hi:[1,0,0]
	v_pk_mul_f32 v[14:15], v[14:15], 0.5 op_sel_hi:[1,0]
	v_pk_add_f32 v[16:17], v[16:17], 1.0 op_sel_hi:[1,0]
	v_pk_mul_f32 v[12:13], v[12:13], 0.5 op_sel_hi:[1,0]
	v_pk_mul_f32 v[46:47], v[14:15], v[16:17]
	v_pk_fma_f32 v[14:15], v[18:19], 2.0, 1.0 op_sel_hi:[1,0,0] neg_lo:[1,0,0] neg_hi:[1,0,0]
	v_mov_b32_e32 v17, v45
	v_pk_add_f32 v[14:15], v[14:15], 1.0 op_sel_hi:[1,0]
	s_nop 0
	v_pk_mul_f32 v[48:49], v[12:13], v[14:15]
	v_mov_b32_e32 v12, v42
	v_mov_b32_e32 v13, v46
	v_mov_b32_e32 v14, v43
	v_mov_b32_e32 v15, v47
	v_pk_add_f32 v[12:13], v[12:13], v[14:15]
	v_mov_b32_e32 v14, v48
	v_mov_b32_e32 v15, v44
	v_mov_b32_e32 v16, v49
	v_pk_add_f32 v[14:15], v[14:15], v[16:17]
	v_add_f32_e32 v12, v12, v13
	v_add_f32_e32 v12, v15, v12
	v_add_f32_e32 v14, v14, v12
	v_mad_i64_i32 v[12:13], s[4:5], v63, s68, v[10:11]
	v_or_b32_e32 v16, 7, v62
	v_mad_i64_i32 v[62:63], s[4:5], v16, s68, v[10:11]
	s_waitcnt lgkmcnt(0)
; __device__ __forceinline__ unsigned f2bf(float f) { unsigned u = __builtin_bit_cast(unsigned, f); return (u + 0x7fffu + ((u >> 16) & 1u)) >> 16; }
; __device__ __forceinline__ void gmlp_item(Frame& F, const Args& a, int l, int chunk, int g, const bf16* P, bf16* ACTA) {
;     ...
;         for (int i = 0; i < 8; ++i) {
;             const int s = w * 16 + i0 + i; f32x4 x0 = xa[i], x1 = xb[i];
; #pragma unroll
;             for (int j = 0; j < 4; ++j) { x0[j] = gelu_tanh(x0[j]); x1[j] = gelu_tanh(x1[j]); }
;             const float mean = wave_sum((x0[0] + x0[1]) + (x0[2] + x0[3]) + (x1[0] + x1[1]) + (x1[2] + x1[3])) * (1.f / 512.f);
;             x0 -= mean; x1 -= mean;
;             const float var = wave_sum((x0[0] * x0[0] + x0[1] * x0[1]) + (x0[2] * x0[2] + x0[3] * x0[3]) + (x1[0] * x1[0] + x1[1] * x1[1]) + (x1[2] * x1[2] + x1[3] * x1[3])) * (1.f / 512.f);
;             const float rstd = 1.0f / sqrtf(var + 1e-5f);
;             const f32x4 xm = myj ? x1 : x0;
;             if ((lane >> 5) == (g & 1)) {
;                 const int cl = 4 * (lane - mylo);
; #pragma unroll
;                 for (int j = 0; j < 4; ++j) Vt[(cl + j) * 136 + s] = (bf16)f2bf(xm[j] * rstd * lgv[j] + lbv[j]);
	s_nop 1
	v_add_f32_dpp v64, v14, v14 quad_perm:[1,0,3,2] row_mask:0xf bank_mask:0xf
	global_load_dwordx2 v[18:19], v[12:13], off offset:1024
	global_load_dwordx2 v[16:17], v[12:13], off offset:1536
	global_load_dwordx2 v[14:15], v[62:63], off offset:1024
	s_nop 0
	global_load_dwordx2 v[12:13], v[62:63], off offset:1536
	s_waitcnt lgkmcnt(0)
	s_nop 1
	v_add_f32_dpp v62, v64, v64 quad_perm:[2,3,0,1] row_mask:0xf bank_mask:0xf
	s_waitcnt lgkmcnt(0)
	s_nop 1
	v_add_f32_dpp v62, v62, v62 row_half_mirror row_mask:0xf bank_mask:0xf
	s_waitcnt lgkmcnt(0)
	s_nop 1
	v_add_f32_dpp v62, v62, v62 row_mirror row_mask:0xf bank_mask:0xf
	s_waitcnt lgkmcnt(0)
	v_mov_b32_e32 v63, v62
	s_nop 1
	v_permlane16_swap_b32 v63, v62
	v_add_f32_e32 v62, v62, v63
	s_waitcnt lgkmcnt(0)
	v_mov_b32_e32 v63, v62
	s_nop 1
	v_permlane32_swap_b32 v63, v62
	v_add_f32_e32 v63, v63, v62
	v_fmamk_f32 v62, v63, 0xbb000000, v47
	v_fmamk_f32 v43, v63, 0xbb000000, v43
	v_fmac_f32_e32 v46, 0xbb000000, v63
	v_fmac_f32_e32 v42, 0xbb000000, v63
	v_fmamk_f32 v49, v63, 0xbb000000, v49
	v_fmac_f32_e32 v48, 0xbb000000, v63
	v_fmamk_f32 v45, v63, 0xbb000000, v45
	v_fmac_f32_e32 v44, 0xbb000000, v63
	v_mul_f32_e32 v47, v43, v43
	v_mul_f32_e32 v63, v62, v62
	v_fmac_f32_e32 v47, v42, v42
	v_fmac_f32_e32 v63, v46, v46
	v_add_f32_e32 v47, v47, v63
	v_mul_f32_e32 v63, v45, v45
	v_fmac_f32_e32 v63, v44, v44
	v_add_f32_e32 v47, v63, v47
	v_mul_f32_e32 v63, v49, v49
	v_fmac_f32_e32 v63, v48, v48
	v_add_f32_e32 v47, v63, v47
	s_waitcnt lgkmcnt(0)
	s_nop 1
	v_add_f32_dpp v47, v47, v47 quad_perm:[1,0,3,2] row_mask:0xf bank_mask:0xf
	s_waitcnt lgkmcnt(0)
	s_nop 1
	v_add_f32_dpp v47, v47, v47 quad_perm:[2,3,0,1] row_mask:0xf bank_mask:0xf
	s_waitcnt lgkmcnt(0)
	s_nop 1
	v_add_f32_dpp v47, v47, v47 row_half_mirror row_mask:0xf bank_mask:0xf
	s_waitcnt lgkmcnt(0)
	s_nop 1
	v_add_f32_dpp v47, v47, v47 row_mirror row_mask:0xf bank_mask:0xf
	s_waitcnt lgkmcnt(0)
	v_mov_b32_e32 v63, v47
	s_nop 1
	v_permlane16_swap_b32 v63, v47
	v_add_f32_e32 v63, v63, v47
	ds_bpermute_b32 v64, v59, v63
	v_lshl_add_u32 v47, s2, 1, v60
	v_add_u32_e32 v47, v47, v61
	s_and_saveexec_b64 s[2:3], s[38:39]
	s_cbranch_execz .LBB0_545
	v_cndmask_b32_e64 v42, v44, v42, s[0:1]
	s_waitcnt lgkmcnt(0)
	v_add_f32_e32 v44, v63, v64
	v_fmamk_f32 v44, v44, 0x3b000000, v215
	v_cndmask_b32_e64 v43, v45, v43, s[0:1]
	v_cmp_gt_f32_e32 vcc, s67, v44
	v_mul_f32_e32 v45, 0x4f800000, v44
	v_cndmask_b32_e64 v46, v48, v46, s[0:1]
	v_cndmask_b32_e32 v44, v44, v45, vcc
	v_sqrt_f32_e32 v45, v44
	v_cndmask_b32_e64 v49, v49, v62, s[0:1]
	v_add_u32_e32 v48, -1, v45
	v_fma_f32 v62, -v48, v45, v44
	v_cmp_ge_f32_e64 s[4:5], 0, v62
	v_add_u32_e32 v62, 1, v45
	s_nop 0
	v_cndmask_b32_e64 v48, v45, v48, s[4:5]
	v_fma_f32 v45, -v62, v45, v44
	v_cmp_lt_f32_e64 s[4:5], 0, v45
	s_nop 1
	v_cndmask_b32_e64 v45, v48, v62, s[4:5]
	v_mul_f32_e32 v48, 0x37800000, v45
	v_cndmask_b32_e32 v45, v45, v48, vcc
	v_cmp_class_f32_e32 vcc, v44, v213
	s_nop 1
	v_cndmask_b32_e32 v44, v45, v44, vcc
	v_div_scale_f32 v45, s[4:5], v44, v44, 1.0
	v_rcp_f32_e32 v48, v45
	s_nop 0
	v_fma_f32 v62, -v45, v48, 1.0
	v_fmac_f32_e32 v48, v62, v48
	v_div_scale_f32 v62, vcc, 1.0, v44, 1.0
	v_mul_f32_e32 v63, v62, v48
	v_fma_f32 v64, -v45, v63, v62
	v_fmac_f32_e32 v63, v64, v48
	v_fma_f32 v45, -v45, v63, v62
	v_div_fmas_f32 v45, v45, v48, v63
	v_div_fixup_f32 v44, v45, v44, 1.0
	v_mul_f32_e32 v42, v42, v44
	v_fma_f32 v42, v2, v42, v6
	v_bfe_u32 v45, v42, 16, 1
	v_add3_u32 v42, v42, v45, s7
	ds_write_b16_d16_hi v47, v42
	v_mul_f32_e32 v42, v43, v44
	v_fma_f32 v42, v3, v42, v7
	v_bfe_u32 v43, v42, 16, 1
	v_add3_u32 v42, v42, v43, s7
	ds_write_b16_d16_hi v47, v42 offset:272
	v_mul_f32_e32 v42, v46, v44
	v_fma_f32 v42, v4, v42, v8
	v_bfe_u32 v43, v42, 16, 1
	v_add3_u32 v42, v42, v43, s7
	ds_write_b16_d16_hi v47, v42 offset:544
	v_mul_f32_e32 v42, v49, v44
	v_fma_f32 v42, v5, v42, v9
	v_bfe_u32 v43, v42, 16, 1
	v_add3_u32 v42, v42, v43, s7
	ds_write_b16_d16_hi v47, v42 offset:816
